# w_in special tile: forget-gate log-sigmoids spread over all 64 lanes (2 per lane instead of 8 on 16 lanes)
# speedup vs baseline: 1.0391x; 1.0100x over previous
; #define PG8_STAGE(bufoff, gbase, voff) do { _Pragma("unroll") for (int _i = 0; _i < 2; ++_i) \
;         __builtin_amdgcn_global_load_lds((const unsigned*)((const char*)(gbase) + (voff)[_i]), (LAS unsigned*)(lds + (bufoff) + ldsw + _i * 8192), 16, 0, 0); } while (0)
; #define PG8_LDA(dst, b, h) do { _Pragma("unroll") for (int m = 0; m < 4; ++m) _Pragma("unroll") for (int k = 0; k < 2; ++k) dst[m][k] = *(const LAS bf16x8*)(lds + PG8_SA(b, h) + aoff + m * 2048 + k * 1024); } while (0)
; #define PG8_WAIT_V(n) asm volatile("s_waitcnt vmcnt(" #n ")" ::: "memory")
; #define PG8_WAIT_L(n) asm volatile("s_waitcnt lgkmcnt(" #n ")" ::: "memory")
; template <class Epi, class Sched>
; __device__ __forceinline__ void gemm_phase(LAS unsigned char* lds, const Gemm g, const Sched& S, const Epi& E) {
;     ...
;         for (int t = 0; t < nt; t += 2) {
;             const bool last = (t == nt - 2);
;             const char* a1 = cA + (size_t)(t + 1) * kstep;
;             const char* a2 = last ? nA : cA + (size_t)(t + 2) * kstep; const char* b2 = last ? nB : cB + (size_t)(t + 2) * kstep;
;             const char* a3 = a2 + kstep; const char* b3 = b2 + kstep;
;             PG8_LDB(B0, 0, 0); PG8_SCHED; PG8_LDA(At, 0, 0); PG8_STAGE(PG8_SA(1, 1), a1 + hstepA, voffA);
;             PG8_WAIT_L(8); PG8_BAR; PG8_WAIT_L(0); PG8_MMA(0, 0, At, B0); PG8_BAR; PG8_SCHED;
;             PG8_LDB(B1, 0, 1); PG8_STAGE(PG8_SB(0, 0), b2, voffB);
;             PG8_BAR; PG8_WAIT_L(0); PG8_MMA(0, 1, At, B1); PG8_BAR;
;             PG8_LDA(At, 0, 1); PG8_STAGE(PG8_SA(0, 0), a2, voffA);
;             PG8_BAR; PG8_WAIT_L(0); PG8_MMA(1, 0, At, B0); PG8_BAR; PG8_SCHED;
;             PG8_STAGE(PG8_SB(0, 1), b2 + hstepB, voffB);
;             PG8_WAIT_V(6); PG8_BAR; PG8_MMA(1, 1, At, B1); PG8_BAR;
;             PG8_LDB(B0, 1, 0); PG8_SCHED; PG8_LDA(At, 1, 0); PG8_STAGE(PG8_SA(0, 1), a2 + hstepA, voffA);
;             PG8_WAIT_L(8); PG8_BAR; PG8_WAIT_L(0); PG8_MMA(0, 0, At, B0); PG8_BAR; PG8_SCHED;
;             PG8_LDB(B1, 1, 1); PG8_STAGE(PG8_SB(1, 0), b3, voffB);
;             PG8_BAR; PG8_WAIT_L(0); PG8_MMA(0, 1, At, B1); PG8_BAR;
;             PG8_LDA(At, 1, 1); PG8_STAGE(PG8_SA(1, 0), a3, voffA);
;             PG8_BAR; PG8_WAIT_L(0); PG8_MMA(1, 0, At, B0); PG8_BAR; PG8_SCHED;
;             PG8_STAGE(PG8_SB(1, 1), b3 + hstepB, voffB);
;             PG8_WAIT_V(6); PG8_BAR; PG8_MMA(1, 1, At, B1); PG8_BAR;
.LBB0_945:
	s_add_u32 s16, s10, 0xfff80080
	s_addc_u32 s17, s11, -1
	s_add_i32 s20, 0, 0x10000
	v_add_u32_e32 v0, s20, v156
	ds_read_b128 v[150:153], v0
	ds_read_b128 v[158:161], v0 offset:1024
	ds_read_b128 v[162:165], v0 offset:2048
	ds_read_b128 v[166:169], v0 offset:3072
	s_cmp_eq_u32 s14, 28
	s_cselect_b32 s19, s2, s17
	s_cselect_b32 s18, s3, s16
	s_cselect_b32 s17, s6, s12
	s_cselect_b32 s16, s7, s9
	v_lshl_add_u64 v[154:155], s[10:11], 0, v[148:149]
	s_add_i32 m0, s47, 0xc000
	ds_read_b128 v[170:173], v157
	ds_read_b128 v[174:177], v157 offset:1024
	ds_read_b128 v[178:181], v157 offset:2048
	ds_read_b128 v[182:185], v157 offset:3072
	ds_read_b128 v[186:189], v157 offset:4096
	ds_read_b128 v[190:193], v157 offset:5120
	ds_read_b128 v[198:201], v157 offset:6144
	ds_read_b128 v[202:205], v157 offset:7168
	global_load_lds_dwordx4 v[154:155], off
	v_lshl_add_u64 v[154:155], s[10:11], 0, v[146:147]
	s_add_i32 m0, s47, 0xe000
	s_nop 0
	global_load_lds_dwordx4 v[154:155], off
	s_waitcnt lgkmcnt(8)
	s_barrier
	s_waitcnt lgkmcnt(0)
	s_setprio 1
	s_waitcnt lgkmcnt(0)
	v_mfma_f32_16x16x32_bf16 v[126:129], v[150:153], v[170:173], v[126:129]
	v_mfma_f32_16x16x32_bf16 v[122:125], v[162:165], v[170:173], v[122:125]
	v_mfma_f32_16x16x32_bf16 v[110:113], v[150:153], v[178:181], v[110:113]
	v_mfma_f32_16x16x32_bf16 v[106:109], v[162:165], v[178:181], v[106:109]
	v_mfma_f32_16x16x32_bf16 v[94:97], v[150:153], v[186:189], v[94:97]
	v_mfma_f32_16x16x32_bf16 v[90:93], v[162:165], v[186:189], v[90:93]
	v_mfma_f32_16x16x32_bf16 v[78:81], v[150:153], v[198:201], v[78:81]
	v_mfma_f32_16x16x32_bf16 v[74:77], v[162:165], v[198:201], v[74:77]
	v_mfma_f32_16x16x32_bf16 v[126:129], v[158:161], v[174:177], v[126:129]
	v_mfma_f32_16x16x32_bf16 v[122:125], v[166:169], v[174:177], v[122:125]
	v_mfma_f32_16x16x32_bf16 v[110:113], v[158:161], v[182:185], v[110:113]
	v_mfma_f32_16x16x32_bf16 v[106:109], v[166:169], v[182:185], v[106:109]
	v_mfma_f32_16x16x32_bf16 v[94:97], v[158:161], v[190:193], v[94:97]
	v_mfma_f32_16x16x32_bf16 v[90:93], v[166:169], v[190:193], v[90:93]
	v_mfma_f32_16x16x32_bf16 v[78:81], v[158:161], v[202:205], v[78:81]
	v_mfma_f32_16x16x32_bf16 v[74:77], v[166:169], v[202:205], v[74:77]
	s_setprio 0
	s_barrier
	s_add_i32 s24, 0, 0x14000
	s_add_i32 s20, s20, s46
	v_add_u32_e32 v0, s24, v156
	v_lshl_add_u64 v[154:155], s[16:17], 0, v[132:133]
	s_mov_b32 m0, s20
	ds_read_b128 v[206:209], v0
	ds_read_b128 v[224:227], v0 offset:1024
	ds_read_b128 v[228:231], v0 offset:2048
	ds_read_b128 v[232:235], v0 offset:3072
	global_load_lds_dwordx4 v[154:155], off
	v_lshl_add_u64 v[194:195], s[16:17], 0, v[136:137]
	s_add_i32 m0, s20, 0x2000
	s_nop 0
	global_load_lds_dwordx4 v[194:195], off
	s_barrier
	s_waitcnt lgkmcnt(0)
	s_setprio 1
	s_waitcnt lgkmcnt(0)
	v_mfma_f32_16x16x32_bf16 v[118:121], v[206:209], v[170:173], v[118:121]
	v_mfma_f32_16x16x32_bf16 v[114:117], v[228:231], v[170:173], v[114:117]
	v_mfma_f32_16x16x32_bf16 v[102:105], v[206:209], v[178:181], v[102:105]
	v_mfma_f32_16x16x32_bf16 v[98:101], v[228:231], v[178:181], v[98:101]
	v_mfma_f32_16x16x32_bf16 v[86:89], v[206:209], v[186:189], v[86:89]
	v_mfma_f32_16x16x32_bf16 v[82:85], v[228:231], v[186:189], v[82:85]
	v_mfma_f32_16x16x32_bf16 v[70:73], v[206:209], v[198:201], v[70:73]
	v_mfma_f32_16x16x32_bf16 v[66:69], v[228:231], v[198:201], v[66:69]
	v_mfma_f32_16x16x32_bf16 v[118:121], v[224:227], v[174:177], v[118:121]
	v_mfma_f32_16x16x32_bf16 v[114:117], v[232:235], v[174:177], v[114:117]
	v_mfma_f32_16x16x32_bf16 v[102:105], v[224:227], v[182:185], v[102:105]
	v_mfma_f32_16x16x32_bf16 v[98:101], v[232:235], v[182:185], v[98:101]
	v_mfma_f32_16x16x32_bf16 v[86:89], v[224:227], v[190:193], v[86:89]
	v_mfma_f32_16x16x32_bf16 v[82:85], v[232:235], v[190:193], v[82:85]
	v_mfma_f32_16x16x32_bf16 v[70:73], v[224:227], v[202:205], v[70:73]
	v_mfma_f32_16x16x32_bf16 v[66:69], v[232:235], v[202:205], v[66:69]
	s_setprio 0
	s_mov_b32 m0, s47
	v_lshl_add_u64 v[196:197], s[18:19], 0, v[130:131]
	s_barrier
	ds_read_b128 v[170:173], v157 offset:16384
	ds_read_b128 v[174:177], v157 offset:17408
	ds_read_b128 v[178:181], v157 offset:18432
	ds_read_b128 v[182:185], v157 offset:19456
	ds_read_b128 v[186:189], v157 offset:20480
	ds_read_b128 v[190:193], v157 offset:21504
	ds_read_b128 v[198:201], v157 offset:22528
	ds_read_b128 v[202:205], v157 offset:23552
	global_load_lds_dwordx4 v[196:197], off
	v_lshl_add_u64 v[236:237], s[18:19], 0, v[134:135]
	s_mov_b32 m0, s72
	s_nop 0
	global_load_lds_dwordx4 v[236:237], off
	s_barrier
	s_waitcnt lgkmcnt(0)
	s_setprio 1
	s_waitcnt lgkmcnt(0)
	v_mfma_f32_16x16x32_bf16 v[62:65], v[150:153], v[170:173], v[62:65]
	v_mfma_f32_16x16x32_bf16 v[58:61], v[162:165], v[170:173], v[58:61]
	v_mfma_f32_16x16x32_bf16 v[46:49], v[150:153], v[178:181], v[46:49]
	v_mfma_f32_16x16x32_bf16 v[42:45], v[162:165], v[178:181], v[42:45]
	v_mfma_f32_16x16x32_bf16 v[30:33], v[150:153], v[186:189], v[30:33]
	v_mfma_f32_16x16x32_bf16 v[26:29], v[162:165], v[186:189], v[26:29]
	v_mfma_f32_16x16x32_bf16 v[14:17], v[150:153], v[198:201], v[14:17]
	v_mfma_f32_16x16x32_bf16 v[10:13], v[162:165], v[198:201], v[10:13]
	v_mfma_f32_16x16x32_bf16 v[62:65], v[158:161], v[174:177], v[62:65]
	v_mfma_f32_16x16x32_bf16 v[58:61], v[166:169], v[174:177], v[58:61]
	v_mfma_f32_16x16x32_bf16 v[46:49], v[158:161], v[182:185], v[46:49]
	v_mfma_f32_16x16x32_bf16 v[42:45], v[166:169], v[182:185], v[42:45]
	v_mfma_f32_16x16x32_bf16 v[30:33], v[158:161], v[190:193], v[30:33]
	v_mfma_f32_16x16x32_bf16 v[26:29], v[166:169], v[190:193], v[26:29]
	v_mfma_f32_16x16x32_bf16 v[14:17], v[158:161], v[202:205], v[14:17]
	v_mfma_f32_16x16x32_bf16 v[10:13], v[166:169], v[202:205], v[10:13]
	s_setprio 0
	s_barrier
; #define PG8_STAGE(bufoff, gbase, voff) do { _Pragma("unroll") for (int _i = 0; _i < 2; ++_i) \
;         __builtin_amdgcn_global_load_lds((const unsigned*)((const char*)(gbase) + (voff)[_i]), (LAS unsigned*)(lds + (bufoff) + ldsw + _i * 8192), 16, 0, 0); } while (0)
; #define PG8_LDA(dst, b, h) do { _Pragma("unroll") for (int m = 0; m < 4; ++m) _Pragma("unroll") for (int k = 0; k < 2; ++k) dst[m][k] = *(const LAS bf16x8*)(lds + PG8_SA(b, h) + aoff + m * 2048 + k * 1024); } while (0)
; #define PG8_LDB(dst, b, h) do { _Pragma("unroll") for (int n = 0; n < 2; ++n) _Pragma("unroll") for (int k = 0; k < 2; ++k) dst[n][k] = *(const LAS bf16x8*)(lds + PG8_SB(b, h) + boff + n * 2048 + k * 1024); } while (0)
; #define PG8_MMA(ai, bj, At, Bt) do { __builtin_amdgcn_s_setprio(1); _Pragma("unroll") for (int m = 0; m < 4; ++m) _Pragma("unroll") for (int n = 0; n < 2; ++n) _Pragma("unroll") for (int k = 0; k < 2; ++k) \
;         acc[ai][bj][m][n] = __builtin_amdgcn_mfma_f32_16x16x32_bf16(Bt[n][k], At[m][k], acc[ai][bj][m][n], 0, 0, 0); __builtin_amdgcn_s_setprio(0); } while (0)
; #define PG8_WAIT_V(n) asm volatile("s_waitcnt vmcnt(" #n ")" ::: "memory")
; #define PG8_WAIT_L(n) asm volatile("s_waitcnt lgkmcnt(" #n ")" ::: "memory")
; template <class Epi, class Sched>
; __device__ __forceinline__ void gemm_phase(LAS unsigned char* lds, const Gemm g, const Sched& S, const Epi& E) {
;     ...
;             PG8_BAR; PG8_WAIT_L(0); PG8_MMA(0, 1, At, B1); PG8_BAR;
;             PG8_LDA(At, 0, 1); PG8_STAGE(PG8_SA(0, 0), a2, voffA);
;             PG8_BAR; PG8_WAIT_L(0); PG8_MMA(1, 0, At, B0); PG8_BAR; PG8_SCHED;
;             PG8_STAGE(PG8_SB(0, 1), b2 + hstepB, voffB);
;             PG8_WAIT_V(6); PG8_BAR; PG8_MMA(1, 1, At, B1); PG8_BAR;
;             PG8_LDB(B0, 1, 0); PG8_SCHED; PG8_LDA(At, 1, 0); PG8_STAGE(PG8_SA(0, 1), a2 + hstepA, voffA);
;             PG8_WAIT_L(8); PG8_BAR; PG8_WAIT_L(0); PG8_MMA(0, 0, At, B0); PG8_BAR; PG8_SCHED;
;             PG8_LDB(B1, 1, 1); PG8_STAGE(PG8_SB(1, 0), b3, voffB);
;             PG8_BAR; PG8_WAIT_L(0); PG8_MMA(0, 1, At, B1); PG8_BAR;
;             PG8_LDA(At, 1, 1); PG8_STAGE(PG8_SA(1, 0), a3, voffA);
;             PG8_BAR; PG8_WAIT_L(0); PG8_MMA(1, 0, At, B0); PG8_BAR; PG8_SCHED;
;             PG8_STAGE(PG8_SB(1, 1), b3 + hstepB, voffB);
;             PG8_WAIT_V(6); PG8_BAR; PG8_MMA(1, 1, At, B1); PG8_BAR;
	s_add_u32 s20, s16, 0x80000
	s_addc_u32 s21, s17, 0
	s_add_i32 s24, s24, s46
	v_lshl_add_u64 v[150:151], s[20:21], 0, v[132:133]
	s_mov_b32 m0, s24
	s_nop 0
	global_load_lds_dwordx4 v[150:151], off
	v_lshl_add_u64 v[150:151], s[20:21], 0, v[136:137]
	s_add_i32 m0, s24, 0x2000
	s_nop 0
	global_load_lds_dwordx4 v[150:151], off
	s_waitcnt vmcnt(6)
	s_barrier
	s_setprio 1
	v_mfma_f32_16x16x32_bf16 v[54:57], v[206:209], v[170:173], v[54:57]
	v_mfma_f32_16x16x32_bf16 v[50:53], v[228:231], v[170:173], v[50:53]
	v_mfma_f32_16x16x32_bf16 v[38:41], v[206:209], v[178:181], v[38:41]
	v_mfma_f32_16x16x32_bf16 v[34:37], v[228:231], v[178:181], v[34:37]
	v_mfma_f32_16x16x32_bf16 v[22:25], v[206:209], v[186:189], v[22:25]
	v_mfma_f32_16x16x32_bf16 v[18:21], v[228:231], v[186:189], v[18:21]
	v_mfma_f32_16x16x32_bf16 v[6:9], v[206:209], v[198:201], v[6:9]
	v_mfma_f32_16x16x32_bf16 v[2:5], v[228:231], v[198:201], v[2:5]
	v_mfma_f32_16x16x32_bf16 v[54:57], v[224:227], v[174:177], v[54:57]
	v_mfma_f32_16x16x32_bf16 v[50:53], v[232:235], v[174:177], v[50:53]
	v_mfma_f32_16x16x32_bf16 v[38:41], v[224:227], v[182:185], v[38:41]
	v_mfma_f32_16x16x32_bf16 v[34:37], v[232:235], v[182:185], v[34:37]
	v_mfma_f32_16x16x32_bf16 v[22:25], v[224:227], v[190:193], v[22:25]
	v_mfma_f32_16x16x32_bf16 v[18:21], v[232:235], v[190:193], v[18:21]
	v_mfma_f32_16x16x32_bf16 v[6:9], v[224:227], v[202:205], v[6:9]
	v_mfma_f32_16x16x32_bf16 v[2:5], v[232:235], v[202:205], v[2:5]
	s_setprio 0
	s_add_i32 s20, 0, 0x18000
	v_add_u32_e32 v0, s20, v156
	s_barrier
	ds_read_b128 v[150:153], v0
	ds_read_b128 v[158:161], v0 offset:1024
	ds_read_b128 v[162:165], v0 offset:2048
	ds_read_b128 v[166:169], v0 offset:3072
	s_add_u32 s18, s18, 0x80000
	s_addc_u32 s19, s19, 0
	s_mov_b32 m0, s73
	v_lshl_add_u64 v[206:207], s[18:19], 0, v[130:131]
	ds_read_b128 v[170:173], v157 offset:32768
	ds_read_b128 v[174:177], v157 offset:33792
	ds_read_b128 v[178:181], v157 offset:34816
	ds_read_b128 v[182:185], v157 offset:35840
	ds_read_b128 v[186:189], v157 offset:36864
	ds_read_b128 v[190:193], v157 offset:37888
	ds_read_b128 v[198:201], v157 offset:38912
	ds_read_b128 v[202:205], v157 offset:39936
	global_load_lds_dwordx4 v[206:207], off
	v_lshl_add_u64 v[206:207], s[18:19], 0, v[134:135]
	s_mov_b32 m0, s74
	s_nop 0
	global_load_lds_dwordx4 v[206:207], off
	s_waitcnt lgkmcnt(8)
	s_barrier
	s_waitcnt lgkmcnt(0)
	s_setprio 1
	s_waitcnt lgkmcnt(0)
	v_mfma_f32_16x16x32_bf16 v[126:129], v[150:153], v[170:173], v[126:129]
	v_mfma_f32_16x16x32_bf16 v[122:125], v[162:165], v[170:173], v[122:125]
	v_mfma_f32_16x16x32_bf16 v[110:113], v[150:153], v[178:181], v[110:113]
	v_mfma_f32_16x16x32_bf16 v[106:109], v[162:165], v[178:181], v[106:109]
	v_mfma_f32_16x16x32_bf16 v[94:97], v[150:153], v[186:189], v[94:97]
	v_mfma_f32_16x16x32_bf16 v[90:93], v[162:165], v[186:189], v[90:93]
	v_mfma_f32_16x16x32_bf16 v[78:81], v[150:153], v[198:201], v[78:81]
	v_mfma_f32_16x16x32_bf16 v[74:77], v[162:165], v[198:201], v[74:77]
	v_mfma_f32_16x16x32_bf16 v[126:129], v[158:161], v[174:177], v[126:129]
	v_mfma_f32_16x16x32_bf16 v[122:125], v[166:169], v[174:177], v[122:125]
	v_mfma_f32_16x16x32_bf16 v[110:113], v[158:161], v[182:185], v[110:113]
	v_mfma_f32_16x16x32_bf16 v[106:109], v[166:169], v[182:185], v[106:109]
	v_mfma_f32_16x16x32_bf16 v[94:97], v[158:161], v[190:193], v[94:97]
	v_mfma_f32_16x16x32_bf16 v[90:93], v[166:169], v[190:193], v[90:93]
	v_mfma_f32_16x16x32_bf16 v[78:81], v[158:161], v[202:205], v[78:81]
	v_mfma_f32_16x16x32_bf16 v[74:77], v[166:169], v[202:205], v[74:77]
	s_setprio 0
	s_barrier
	s_add_i32 s18, 0, 0x1c000
	s_add_i32 s19, s20, s46
	v_add_u32_e32 v0, s18, v156
	v_lshl_add_u64 v[154:155], v[154:155], 0, s[26:27]
	s_mov_b32 m0, s19
	ds_read_b128 v[206:209], v0
	ds_read_b128 v[224:227], v0 offset:1024
	ds_read_b128 v[228:231], v0 offset:2048
	ds_read_b128 v[232:235], v0 offset:3072
	global_load_lds_dwordx4 v[154:155], off
	v_lshl_add_u64 v[154:155], v[194:195], 0, s[26:27]
	s_add_i32 m0, s19, 0x2000
	s_nop 0
	global_load_lds_dwordx4 v[154:155], off
	s_barrier
	s_waitcnt lgkmcnt(0)
	s_setprio 1
	s_waitcnt lgkmcnt(0)
	v_mfma_f32_16x16x32_bf16 v[118:121], v[206:209], v[170:173], v[118:121]
	v_mfma_f32_16x16x32_bf16 v[114:117], v[228:231], v[170:173], v[114:117]
	v_mfma_f32_16x16x32_bf16 v[102:105], v[206:209], v[178:181], v[102:105]
	v_mfma_f32_16x16x32_bf16 v[98:101], v[228:231], v[178:181], v[98:101]
	v_mfma_f32_16x16x32_bf16 v[86:89], v[206:209], v[186:189], v[86:89]
	v_mfma_f32_16x16x32_bf16 v[82:85], v[228:231], v[186:189], v[82:85]
	v_mfma_f32_16x16x32_bf16 v[70:73], v[206:209], v[198:201], v[70:73]
	v_mfma_f32_16x16x32_bf16 v[66:69], v[228:231], v[198:201], v[66:69]
	v_mfma_f32_16x16x32_bf16 v[118:121], v[224:227], v[174:177], v[118:121]
	v_mfma_f32_16x16x32_bf16 v[114:117], v[232:235], v[174:177], v[114:117]
	v_mfma_f32_16x16x32_bf16 v[102:105], v[224:227], v[182:185], v[102:105]
	v_mfma_f32_16x16x32_bf16 v[98:101], v[232:235], v[182:185], v[98:101]
	v_mfma_f32_16x16x32_bf16 v[86:89], v[224:227], v[190:193], v[86:89]
	v_mfma_f32_16x16x32_bf16 v[82:85], v[232:235], v[190:193], v[82:85]
	v_mfma_f32_16x16x32_bf16 v[70:73], v[224:227], v[202:205], v[70:73]
	v_mfma_f32_16x16x32_bf16 v[66:69], v[232:235], v[202:205], v[66:69]
	s_setprio 0
	s_mov_b32 m0, s77
	v_lshl_add_u64 v[154:155], v[196:197], 0, s[26:27]
	s_barrier
	ds_read_b128 v[170:173], v157 offset:49152
	ds_read_b128 v[174:177], v157 offset:50176
	ds_read_b128 v[178:181], v157 offset:51200
	ds_read_b128 v[182:185], v157 offset:52224
	ds_read_b128 v[186:189], v157 offset:53248
	ds_read_b128 v[190:193], v157 offset:54272
	ds_read_b128 v[198:201], v157 offset:55296
	ds_read_b128 v[202:205], v157 offset:56320
	global_load_lds_dwordx4 v[154:155], off
	v_lshl_add_u64 v[154:155], v[236:237], 0, s[26:27]
	s_mov_b32 m0, s78
	s_nop 0
	global_load_lds_dwordx4 v[154:155], off
	s_barrier
; #define PG8_WAIT_V(n) asm volatile("s_waitcnt vmcnt(" #n ")" ::: "memory")
; #define PG8_BAR __builtin_amdgcn_s_barrier()
; template <class Epi, class Sched>
; __device__ __forceinline__ void gemm_phase(LAS unsigned char* lds, const Gemm g, const Sched& S, const Epi& E) {
;     ...
;             PG8_WAIT_V(6); PG8_BAR; PG8_MMA(1, 1, At, B1); PG8_BAR;
;             PG8_LDB(B0, 1, 0); PG8_SCHED; PG8_LDA(At, 1, 0); PG8_STAGE(PG8_SA(0, 1), a2 + hstepA, voffA);
;             PG8_WAIT_L(8); PG8_BAR; PG8_WAIT_L(0); PG8_MMA(0, 0, At, B0); PG8_BAR; PG8_SCHED;
;             PG8_LDB(B1, 1, 1); PG8_STAGE(PG8_SB(1, 0), b3, voffB);
;             PG8_BAR; PG8_WAIT_L(0); PG8_MMA(0, 1, At, B1); PG8_BAR;
;             PG8_LDA(At, 1, 1); PG8_STAGE(PG8_SA(1, 0), a3, voffA);
;             PG8_BAR; PG8_WAIT_L(0); PG8_MMA(1, 0, At, B0); PG8_BAR; PG8_SCHED;
;             PG8_STAGE(PG8_SB(1, 1), b3 + hstepB, voffB);
;             PG8_WAIT_V(6); PG8_BAR; PG8_MMA(1, 1, At, B1); PG8_BAR;
;         }
;         E(acc, cur, wr, wc, fr, fq);
;         if (!has_next) break;
;     __device__ __forceinline__ void operator()(const AccT& acc, const pg8::Unit& u, int wr, int wc, int fr, int fq) const {
;     ...
;                     if (wc == 0) {
;                         const f32x4 c0 = *(const f32x4*)(cosT + row * 32 + 8 * fq), c1 = *(const f32x4*)(cosT + row * 32 + 8 * fq + 4);
;                         const f32x4 s0 = *(const f32x4*)(sinT + row * 32 + 8 * fq), s1 = *(const f32x4*)(sinT + row * 32 + 8 * fq + 4);
;                         const f32x4 x1a = acc[ai][0][m][0] * rs, x1b = acc[ai][0][m][1] * rs, x2a = acc[ai][1][m][0] * rs, x2b = acc[ai][1][m][1] * rs;
;                         const f32x4 y1a = x1a * c0 - x2a * s0, y1b = x1b * c1 - x2b * s1, y2a = x2a * c0 + x1a * s0, y2b = x2b * c1 + x1b * s1;
;                         *(u32x4*)(Kr + (size_t)row * 64 + 8 * fq) = pack8s(y1a, y1b, 1.0f);
;                         *(u32x4*)(Kr + (size_t)row * 64 + 32 + 8 * fq) = pack8s(y2a, y2b, 1.0f);
;                     } else if (wc == 1 && fq == 0) {
; #pragma unroll
;                         for (int n = 0; n < 2; ++n)
; #pragma unroll
;                             for (int j = 0; j < 4; ++j) {
;                                 const float x = acc[ai][0][m][n][j] * rs + bfg[4 * n + j];
;                                 lf[(4 * n + j) * MROWS + row] = fminf(x, 0.f) - log1pf(__expf(-fabsf(x)));
	s_waitcnt lgkmcnt(0)
	s_setprio 1
	s_waitcnt lgkmcnt(0)
	v_mfma_f32_16x16x32_bf16 v[62:65], v[150:153], v[170:173], v[62:65]
	v_mfma_f32_16x16x32_bf16 v[58:61], v[162:165], v[170:173], v[58:61]
	v_mfma_f32_16x16x32_bf16 v[46:49], v[150:153], v[178:181], v[46:49]
	v_mfma_f32_16x16x32_bf16 v[42:45], v[162:165], v[178:181], v[42:45]
	v_mfma_f32_16x16x32_bf16 v[30:33], v[150:153], v[186:189], v[30:33]
	v_mfma_f32_16x16x32_bf16 v[26:29], v[162:165], v[186:189], v[26:29]
	v_mfma_f32_16x16x32_bf16 v[14:17], v[150:153], v[198:201], v[14:17]
	v_mfma_f32_16x16x32_bf16 v[10:13], v[162:165], v[198:201], v[10:13]
	v_mfma_f32_16x16x32_bf16 v[62:65], v[158:161], v[174:177], v[62:65]
	v_mfma_f32_16x16x32_bf16 v[58:61], v[166:169], v[174:177], v[58:61]
	v_mfma_f32_16x16x32_bf16 v[46:49], v[158:161], v[182:185], v[46:49]
	v_mfma_f32_16x16x32_bf16 v[42:45], v[166:169], v[182:185], v[42:45]
	v_mfma_f32_16x16x32_bf16 v[30:33], v[158:161], v[190:193], v[30:33]
	v_mfma_f32_16x16x32_bf16 v[26:29], v[166:169], v[190:193], v[26:29]
	v_mfma_f32_16x16x32_bf16 v[14:17], v[158:161], v[202:205], v[14:17]
	v_mfma_f32_16x16x32_bf16 v[10:13], v[166:169], v[202:205], v[10:13]
	s_setprio 0
	s_barrier
	s_add_u32 s16, s16, 0x80080
	s_addc_u32 s17, s17, 0
	s_add_i32 s18, s18, s46
	v_lshl_add_u64 v[150:151], s[16:17], 0, v[132:133]
	s_mov_b32 m0, s18
	s_nop 0
	global_load_lds_dwordx4 v[150:151], off
	v_lshl_add_u64 v[150:151], s[16:17], 0, v[136:137]
	s_add_i32 m0, s18, 0x2000
	s_nop 0
	global_load_lds_dwordx4 v[150:151], off
	s_waitcnt vmcnt(6)
	s_barrier
	s_setprio 1
	v_mfma_f32_16x16x32_bf16 v[54:57], v[206:209], v[170:173], v[54:57]
	v_mfma_f32_16x16x32_bf16 v[50:53], v[228:231], v[170:173], v[50:53]
	v_mfma_f32_16x16x32_bf16 v[38:41], v[206:209], v[178:181], v[38:41]
	v_mfma_f32_16x16x32_bf16 v[34:37], v[228:231], v[178:181], v[34:37]
	v_mfma_f32_16x16x32_bf16 v[22:25], v[206:209], v[186:189], v[22:25]
	v_mfma_f32_16x16x32_bf16 v[18:21], v[228:231], v[186:189], v[18:21]
	v_mfma_f32_16x16x32_bf16 v[6:9], v[206:209], v[198:201], v[6:9]
	v_mfma_f32_16x16x32_bf16 v[2:5], v[228:231], v[198:201], v[2:5]
	v_mfma_f32_16x16x32_bf16 v[54:57], v[224:227], v[174:177], v[54:57]
	v_mfma_f32_16x16x32_bf16 v[50:53], v[232:235], v[174:177], v[50:53]
	v_mfma_f32_16x16x32_bf16 v[38:41], v[224:227], v[182:185], v[38:41]
	v_mfma_f32_16x16x32_bf16 v[34:37], v[232:235], v[182:185], v[34:37]
	v_mfma_f32_16x16x32_bf16 v[22:25], v[224:227], v[190:193], v[22:25]
	v_mfma_f32_16x16x32_bf16 v[18:21], v[232:235], v[190:193], v[18:21]
	v_mfma_f32_16x16x32_bf16 v[6:9], v[224:227], v[202:205], v[6:9]
	v_mfma_f32_16x16x32_bf16 v[2:5], v[232:235], v[202:205], v[2:5]
	s_setprio 0
	s_add_i32 s14, s14, 2
	s_add_u32 s9, s9, 0x100
	s_addc_u32 s12, s12, 0
	s_add_u32 s10, s10, 0x100
	s_addc_u32 s11, s11, 0
	s_cmp_gt_u32 s14, 29
	s_barrier
	s_cbranch_scc0 .LBB0_945
	s_cmp_gt_i32 s40, 19
	s_cselect_b64 s[42:43], -1, 0
	s_cmp_lt_i32 s40, 4
	v_lshl_add_u32 v150, s8, 8, v139
	s_cselect_b64 s[44:45], -1, 0
	s_mov_b64 s[8:9], -1
	s_and_b64 vcc, exec, s[42:43]
	s_cbranch_vccz .LBB0_954
	s_and_b64 vcc, exec, s[56:57]
	s_cbranch_vccz .LBB0_951
	s_mov_b64 s[68:69], exec
	s_and_b64 s[100:101], exec, s[58:59]
	s_cbranch_scc0 .LBB0_950
	global_load_dword v240, v1, s[54:55]
	global_load_dword v241, v1, s[54:55] offset:4
	global_load_dword v242, v1, s[54:55] offset:8
	global_load_dword v243, v1, s[54:55] offset:12
	global_load_dword v244, v1, s[54:55] offset:16
	global_load_dword v245, v1, s[54:55] offset:20
	global_load_dword v246, v1, s[54:55] offset:24
	global_load_dword v247, v1, s[54:55] offset:28
	v_lshrrev_b32_e32 v239, 4, v215
	v_and_b32_e32 v250, 15, v215
	v_lshlrev_b32_e32 v250, 2, v250
	s_waitcnt vmcnt(0)
	v_mov_b32_e32 v223, v240
	v_mov_b32_e32 v238, v241
	v_cmp_eq_u32_e32 vcc, 1, v239
	s_nop 1
	v_cndmask_b32_e32 v223, v223, v242, vcc
	v_cndmask_b32_e32 v238, v238, v243, vcc
	v_cmp_eq_u32_e32 vcc, 2, v239
	s_nop 1
	v_cndmask_b32_e32 v223, v223, v244, vcc
	v_cndmask_b32_e32 v238, v238, v245, vcc
	v_cmp_eq_u32_e32 vcc, 3, v239
	s_nop 1
	v_cndmask_b32_e32 v223, v223, v246, vcc
	v_cndmask_b32_e32 v238, v238, v247, vcc
	s_mov_b32 s3, 0xbfb8aa3b
	s_mov_b32 s6, 0x3f2aaaab
	s_mov_b32 s7, 0x3f317218
	s_mov_b32 s8, 0x7f800000
	s_mov_b32 s9, 0x33800000
	s_mov_b32 s2, 0x8000
	s_waitcnt lgkmcnt(0)
	ds_bpermute_b32 v126, v250, v126
	ds_bpermute_b32 v127, v250, v127
	ds_bpermute_b32 v128, v250, v128
	ds_bpermute_b32 v129, v250, v129
	ds_bpermute_b32 v122, v250, v122
	ds_bpermute_b32 v123, v250, v123
	ds_bpermute_b32 v124, v250, v124
	ds_bpermute_b32 v125, v250, v125
	s_mov_b32 s100, 0x10800
	v_lshlrev_b32_e32 v251, 2, v150
	s_waitcnt lgkmcnt(0)
;     __device__ __forceinline__ void operator()(const AccT& acc, const pg8::Unit& u, int wr, int wc, int fr, int fq) const {
;     ...
;                     } else if (wc == 1 && fq == 0) {
; #pragma unroll
;                         for (int n = 0; n < 2; ++n)
; #pragma unroll
;                             for (int j = 0; j < 4; ++j) {
;                                 const float x = acc[ai][0][m][n][j] * rs + bfg[4 * n + j];
;                                 lf[(4 * n + j) * MROWS + row] = fminf(x, 0.f) - log1pf(__expf(-fabsf(x)));
	v_mov_b32_e32 v248, v126
	v_mov_b32_e32 v249, v127
	v_cmp_eq_u32_e32 vcc, 1, v239
	s_nop 1
	v_cndmask_b32_e32 v248, v248, v128, vcc
	v_cndmask_b32_e32 v249, v249, v129, vcc
	v_cmp_eq_u32_e32 vcc, 2, v239
	s_nop 1
	v_cndmask_b32_e32 v248, v248, v122, vcc
	v_cndmask_b32_e32 v249, v249, v123, vcc
	v_cmp_eq_u32_e32 vcc, 3, v239
	s_nop 1
	v_cndmask_b32_e32 v248, v248, v124, vcc
	v_cndmask_b32_e32 v249, v249, v125, vcc
	v_mad_u32_u24 v251, v239, s100, v251
	v_add_u32_e32 v246, 0x8400, v251
	v_add_f32_e32 v0, v248, v223
	v_min_f32_e32 v151, 0, v0
	v_mul_f32_e64 v0, |v0|, s3
	v_exp_f32_e32 v0, v0
	s_nop 0
	v_add_f32_e32 v154, 1.0, v0
	v_add_f32_e32 v152, -1.0, v154
	v_sub_f32_e32 v153, v152, v154
	v_add_f32_e32 v153, 1.0, v153
	v_sub_f32_e32 v152, v0, v152
	v_add_f32_e32 v155, v152, v153
	v_frexp_mant_f32_e32 v152, v154
	v_cmp_gt_f32_e32 vcc, s6, v152
	v_cvt_f64_f32_e32 v[152:153], v154
	v_frexp_exp_i32_f64_e32 v152, v[152:153]
	v_subbrev_co_u32_e32 v152, vcc, 0, v152, vcc
	v_sub_u32_e32 v153, 0, v152
	v_ldexp_f32 v154, v154, v153
	v_ldexp_f32 v153, v155, v153
	v_add_f32_e32 v155, -1.0, v154
	v_add_f32_e32 v158, 1.0, v155
	v_sub_f32_e32 v158, v154, v158
	v_add_f32_e32 v158, v153, v158
	v_add_f32_e32 v159, v155, v158
	v_sub_f32_e32 v155, v159, v155
	v_sub_f32_e32 v155, v158, v155
	v_add_f32_e32 v158, 1.0, v154
	v_add_f32_e32 v160, -1.0, v158
	v_sub_f32_e32 v154, v154, v160
	v_add_f32_e32 v153, v153, v154
	v_add_f32_e32 v154, v158, v153
	v_sub_f32_e32 v158, v154, v158
	v_sub_f32_e32 v153, v153, v158
	v_rcp_f32_e32 v158, v154
	v_cvt_f32_i32_e32 v152, v152
	v_cmp_neq_f32_e32 vcc, s8, v0
	v_mul_f32_e32 v160, v159, v158
	v_mul_f32_e32 v161, v154, v160
	v_fma_f32 v162, v160, v154, -v161
	v_fmac_f32_e32 v162, v160, v153
	v_add_f32_e32 v163, v161, v162
	v_sub_f32_e32 v164, v159, v163
	v_sub_f32_e32 v159, v159, v164
	v_sub_f32_e32 v161, v163, v161
	v_sub_f32_e32 v159, v159, v163
	v_add_f32_e32 v155, v155, v159
	v_sub_f32_e32 v159, v161, v162
	v_add_f32_e32 v155, v159, v155
	v_add_f32_e32 v159, v164, v155
	v_mul_f32_e32 v161, v158, v159
	v_mul_f32_e32 v162, v154, v161
	v_fma_f32 v154, v161, v154, -v162
	v_fmac_f32_e32 v154, v161, v153
	v_sub_f32_e32 v153, v164, v159
	v_add_f32_e32 v153, v155, v153
	v_add_f32_e32 v155, v162, v154
	v_sub_f32_e32 v163, v159, v155
	v_sub_f32_e32 v159, v159, v163
	v_sub_f32_e32 v162, v155, v162
	v_sub_f32_e32 v155, v159, v155
	v_add_f32_e32 v153, v153, v155
	v_sub_f32_e32 v154, v162, v154
	v_add_f32_e32 v153, v154, v153
	v_add_f32_e32 v154, v160, v161
	v_add_f32_e32 v153, v163, v153
	v_sub_f32_e32 v155, v154, v160
	v_mul_f32_e32 v153, v158, v153
	v_sub_f32_e32 v155, v161, v155
	v_add_f32_e32 v153, v155, v153
	v_mul_f32_e32 v160, 0x3f317218, v152
	v_add_f32_e32 v155, v154, v153
	v_fma_f32 v161, v152, s7, -v160
	v_mul_f32_e32 v158, v155, v155
	v_fmac_f32_e32 v161, 0xb102e308, v152
	v_sub_f32_e32 v152, v155, v154
	v_fmamk_f32 v159, v158, 0x3e9b6dac, v214
	v_sub_f32_e32 v152, v153, v152
	v_add_f32_e32 v153, v160, v161
	v_fmaak_f32 v159, v158, v159, 0x3f2aaada
	v_sub_f32_e32 v154, v153, v160
	v_ldexp_f32 v160, v155, 1
	v_mul_f32_e32 v155, v155, v158
	v_mul_f32_e32 v155, v155, v159
	v_add_f32_e32 v158, v160, v155
	v_sub_f32_e32 v159, v158, v160
	v_ldexp_f32 v152, v152, 1
	v_sub_f32_e32 v155, v155, v159
	v_add_f32_e32 v152, v152, v155
	v_add_f32_e32 v155, v158, v152
	v_sub_f32_e32 v158, v155, v158
	v_sub_f32_e32 v152, v152, v158
	v_add_f32_e32 v158, v153, v155
	v_sub_f32_e32 v159, v158, v153
	v_sub_f32_e32 v160, v158, v159
	v_sub_f32_e32 v154, v161, v154
	v_sub_f32_e32 v153, v153, v160
	v_sub_f32_e32 v155, v155, v159
	v_add_f32_e32 v153, v155, v153
	v_add_f32_e32 v155, v154, v152
	v_sub_f32_e32 v159, v155, v154
	v_sub_f32_e32 v160, v155, v159
	v_sub_f32_e32 v154, v154, v160
	v_sub_f32_e32 v152, v152, v159
	v_add_f32_e32 v153, v155, v153
	v_add_f32_e32 v152, v152, v154
	v_add_f32_e32 v154, v158, v153
	v_sub_f32_e32 v155, v154, v158
	v_sub_f32_e32 v153, v153, v155
	v_add_f32_e32 v152, v152, v153
	v_add_f32_e32 v152, v154, v152
	v_cndmask_b32_e32 v152, v221, v152, vcc
	v_cmp_ngt_f32_e32 vcc, -1.0, v0
	s_nop 1
	v_cndmask_b32_e32 v152, v222, v152, vcc
;     __device__ __forceinline__ void operator()(const AccT& acc, const pg8::Unit& u, int wr, int wc, int fr, int fq) const {
;     ...
;                             for (int j = 0; j < 4; ++j) {
;                                 const float x = acc[ai][0][m][n][j] * rs + bfg[4 * n + j];
;                                 lf[(4 * n + j) * MROWS + row] = fminf(x, 0.f) - log1pf(__expf(-fabsf(x)));
	v_cmp_neq_f32_e32 vcc, -1.0, v0
	s_nop 1
	v_cndmask_b32_e32 v152, v219, v152, vcc
	v_cmp_lt_f32_e64 vcc, |v0|, s9
	s_nop 1
	v_cndmask_b32_e32 v0, v152, v0, vcc
	v_sub_f32_e32 v0, v151, v0
	global_store_dword v251, v0, s[52:53]
	v_add_f32_e32 v0, v249, v238
	v_min_f32_e32 v151, 0, v0
	v_mul_f32_e64 v0, |v0|, s3
	v_exp_f32_e32 v0, v0
	s_nop 0
	v_add_f32_e32 v154, 1.0, v0
	v_add_f32_e32 v152, -1.0, v154
	v_sub_f32_e32 v153, v152, v154
	v_add_f32_e32 v153, 1.0, v153
	v_sub_f32_e32 v152, v0, v152
	v_add_f32_e32 v155, v152, v153
	v_frexp_mant_f32_e32 v152, v154
	v_cmp_gt_f32_e32 vcc, s6, v152
	v_cvt_f64_f32_e32 v[152:153], v154
	v_frexp_exp_i32_f64_e32 v152, v[152:153]
	v_subbrev_co_u32_e32 v152, vcc, 0, v152, vcc
	v_sub_u32_e32 v153, 0, v152
	v_ldexp_f32 v154, v154, v153
	v_ldexp_f32 v153, v155, v153
	v_add_f32_e32 v155, -1.0, v154
	v_add_f32_e32 v158, 1.0, v155
	v_sub_f32_e32 v158, v154, v158
	v_add_f32_e32 v158, v153, v158
	v_add_f32_e32 v159, v155, v158
	v_sub_f32_e32 v155, v159, v155
	v_sub_f32_e32 v155, v158, v155
	v_add_f32_e32 v158, 1.0, v154
	v_add_f32_e32 v160, -1.0, v158
	v_sub_f32_e32 v154, v154, v160
	v_add_f32_e32 v153, v153, v154
	v_add_f32_e32 v154, v158, v153
	v_sub_f32_e32 v158, v154, v158
	v_sub_f32_e32 v153, v153, v158
	v_rcp_f32_e32 v158, v154
	v_cvt_f32_i32_e32 v152, v152
	v_cmp_neq_f32_e32 vcc, s8, v0
	v_mul_f32_e32 v160, v159, v158
	v_mul_f32_e32 v161, v154, v160
	v_fma_f32 v162, v160, v154, -v161
	v_fmac_f32_e32 v162, v160, v153
	v_add_f32_e32 v163, v161, v162
	v_sub_f32_e32 v164, v159, v163
	v_sub_f32_e32 v159, v159, v164
	v_sub_f32_e32 v161, v163, v161
	v_sub_f32_e32 v159, v159, v163
	v_add_f32_e32 v155, v155, v159
	v_sub_f32_e32 v159, v161, v162
	v_add_f32_e32 v155, v159, v155
	v_add_f32_e32 v159, v164, v155
	v_mul_f32_e32 v161, v158, v159
	v_mul_f32_e32 v162, v154, v161
	v_fma_f32 v154, v161, v154, -v162
	v_fmac_f32_e32 v154, v161, v153
	v_sub_f32_e32 v153, v164, v159
	v_add_f32_e32 v153, v155, v153
	v_add_f32_e32 v155, v162, v154
	v_sub_f32_e32 v163, v159, v155
	v_sub_f32_e32 v159, v159, v163
	v_sub_f32_e32 v162, v155, v162
	v_sub_f32_e32 v155, v159, v155
	v_add_f32_e32 v153, v153, v155
	v_sub_f32_e32 v154, v162, v154
	v_add_f32_e32 v153, v154, v153
	v_add_f32_e32 v154, v160, v161
	v_add_f32_e32 v153, v163, v153
	v_sub_f32_e32 v155, v154, v160
	v_mul_f32_e32 v153, v158, v153
	v_sub_f32_e32 v155, v161, v155
	v_add_f32_e32 v153, v155, v153
	v_mul_f32_e32 v160, 0x3f317218, v152
	v_add_f32_e32 v155, v154, v153
	v_fma_f32 v161, v152, s7, -v160
	v_mul_f32_e32 v158, v155, v155
	v_fmac_f32_e32 v161, 0xb102e308, v152
	v_sub_f32_e32 v152, v155, v154
	v_fmamk_f32 v159, v158, 0x3e9b6dac, v214
	v_sub_f32_e32 v152, v153, v152
	v_add_f32_e32 v153, v160, v161
	v_fmaak_f32 v159, v158, v159, 0x3f2aaada
	v_sub_f32_e32 v154, v153, v160
	v_ldexp_f32 v160, v155, 1
	v_mul_f32_e32 v155, v155, v158
	v_mul_f32_e32 v155, v155, v159
	v_add_f32_e32 v158, v160, v155
	v_sub_f32_e32 v159, v158, v160
	v_ldexp_f32 v152, v152, 1
	v_sub_f32_e32 v155, v155, v159
	v_add_f32_e32 v152, v152, v155
	v_add_f32_e32 v155, v158, v152
	v_sub_f32_e32 v158, v155, v158
	v_sub_f32_e32 v152, v152, v158
	v_add_f32_e32 v158, v153, v155
	v_sub_f32_e32 v159, v158, v153
	v_sub_f32_e32 v160, v158, v159
	v_sub_f32_e32 v154, v161, v154
	v_sub_f32_e32 v153, v153, v160
	v_sub_f32_e32 v155, v155, v159
	v_add_f32_e32 v153, v155, v153
	v_add_f32_e32 v155, v154, v152
	v_sub_f32_e32 v159, v155, v154
	v_sub_f32_e32 v160, v155, v159
	v_sub_f32_e32 v154, v154, v160
	v_sub_f32_e32 v152, v152, v159
	v_add_f32_e32 v153, v155, v153
	v_add_f32_e32 v152, v152, v154
	v_add_f32_e32 v154, v158, v153
	v_sub_f32_e32 v155, v154, v158
	v_sub_f32_e32 v153, v153, v155
	v_add_f32_e32 v152, v152, v153
	v_add_f32_e32 v152, v154, v152
	v_cndmask_b32_e32 v152, v221, v152, vcc
	v_cmp_ngt_f32_e32 vcc, -1.0, v0
	s_nop 1
	v_cndmask_b32_e32 v152, v222, v152, vcc
	v_cmp_neq_f32_e32 vcc, -1.0, v0
	s_nop 1
	v_cndmask_b32_e32 v152, v219, v152, vcc
	v_cmp_lt_f32_e64 vcc, |v0|, s9
	s_nop 1
	v_cndmask_b32_e32 v0, v152, v0, vcc
	v_sub_f32_e32 v0, v151, v0
	global_store_dword v246, v0, s[52:53]

;     __device__ __forceinline__ void operator()(const AccT& acc, const pg8::Unit& u, int wr, int wc, int fr, int fq) const {
;     ...
;         for (int ai = 0; ai < 2; ++ai)
; #pragma unroll
;             for (int m = 0; m < 4; ++m) {
;                 const int row = row0 + ai * 128 + m * 16;
;                 const float rs = 1.0f;
;                 if (u.pn < 20) {
;     ...
;                     } else if (wc == 1 && fq == 0) {
; #pragma unroll
;                         for (int n = 0; n < 2; ++n)
; #pragma unroll
;                             for (int j = 0; j < 4; ++j) {
;                                 const float x = acc[ai][0][m][n][j] * rs + bfg[4 * n + j];
;                                 lf[(4 * n + j) * MROWS + row] = fminf(x, 0.f) - log1pf(__expf(-fabsf(x)));
.LBB0_959:
	s_waitcnt lgkmcnt(0)
	v_cndmask_b32_e64 v115, 0, 1, s[42:43]
	v_cmp_ne_u32_e64 s[44:45], 1, v115
	v_cndmask_b32_e64 v115, 0, 1, s[56:57]
	v_or_b32_e32 v114, 16, v150
	s_mov_b64 s[8:9], -1
	s_andn2_b64 vcc, exec, s[42:43]
	v_cmp_ne_u32_e64 s[42:43], 1, v115
	s_cbranch_vccnz .LBB0_967
	s_and_b64 vcc, exec, s[42:43]
	s_cbranch_vccnz .LBB0_964
	s_mov_b64 s[70:71], exec
	s_and_b64 s[100:101], exec, s[58:59]
	s_cbranch_scc0 .LBB0_963
	s_mov_b32 s3, 0xbfb8aa3b
	s_mov_b32 s6, 0x3f2aaaab
	s_mov_b32 s7, 0x3f317218
	s_mov_b32 s8, 0x7f800000
	s_mov_b32 s9, 0x33800000
	s_mov_b32 s2, 0x8000
	s_waitcnt lgkmcnt(0)
	ds_bpermute_b32 v110, v250, v110
	ds_bpermute_b32 v111, v250, v111
	ds_bpermute_b32 v112, v250, v112
	ds_bpermute_b32 v113, v250, v113
	ds_bpermute_b32 v106, v250, v106
	ds_bpermute_b32 v107, v250, v107
	ds_bpermute_b32 v108, v250, v108
	ds_bpermute_b32 v109, v250, v109
	s_mov_b32 s100, 0x10800
	v_lshlrev_b32_e32 v251, 2, v114
	s_waitcnt lgkmcnt(0)
	v_mov_b32_e32 v248, v110
	v_mov_b32_e32 v249, v111
	v_cmp_eq_u32_e32 vcc, 1, v239
	s_nop 1
	v_cndmask_b32_e32 v248, v248, v112, vcc
	v_cndmask_b32_e32 v249, v249, v113, vcc
	v_cmp_eq_u32_e32 vcc, 2, v239
	s_nop 1
	v_cndmask_b32_e32 v248, v248, v106, vcc
	v_cndmask_b32_e32 v249, v249, v107, vcc
	v_cmp_eq_u32_e32 vcc, 3, v239
	s_nop 1
	v_cndmask_b32_e32 v248, v248, v108, vcc
	v_cndmask_b32_e32 v249, v249, v109, vcc
	v_mad_u32_u24 v251, v239, s100, v251
	v_add_u32_e32 v246, 0x8400, v251
	v_add_f32_e32 v115, v248, v223
	v_min_f32_e32 v118, 0, v115
	v_mul_f32_e64 v115, |v115|, s3
	v_exp_f32_e32 v115, v115
	s_nop 0
	v_add_f32_e32 v119, 1.0, v115
	v_add_f32_e32 v116, -1.0, v119
	v_sub_f32_e32 v117, v116, v119
	v_add_f32_e32 v117, 1.0, v117
	v_sub_f32_e32 v116, v115, v116
	v_add_f32_e32 v120, v116, v117
	v_frexp_mant_f32_e32 v116, v119
	v_cmp_gt_f32_e32 vcc, s6, v116
	v_cvt_f64_f32_e32 v[116:117], v119
	v_frexp_exp_i32_f64_e32 v116, v[116:117]
	v_subbrev_co_u32_e32 v116, vcc, 0, v116, vcc
	v_sub_u32_e32 v117, 0, v116
	v_ldexp_f32 v119, v119, v117
	v_ldexp_f32 v117, v120, v117
	v_add_f32_e32 v120, -1.0, v119
	v_add_f32_e32 v121, 1.0, v120
	v_sub_f32_e32 v121, v119, v121
	v_add_f32_e32 v121, v117, v121
	v_add_f32_e32 v122, v120, v121
	v_sub_f32_e32 v120, v122, v120
	v_sub_f32_e32 v120, v121, v120
	v_add_f32_e32 v121, 1.0, v119
	v_add_f32_e32 v123, -1.0, v121
	v_sub_f32_e32 v119, v119, v123
	v_add_f32_e32 v117, v117, v119
	v_add_f32_e32 v119, v121, v117
	v_sub_f32_e32 v121, v119, v121
	v_sub_f32_e32 v117, v117, v121
	v_rcp_f32_e32 v121, v119
	v_cvt_f32_i32_e32 v116, v116
	v_cmp_neq_f32_e32 vcc, s8, v115
	v_mul_f32_e32 v123, v122, v121
	v_mul_f32_e32 v124, v119, v123
	v_fma_f32 v125, v123, v119, -v124
	v_fmac_f32_e32 v125, v123, v117
	v_add_f32_e32 v126, v124, v125
	v_sub_f32_e32 v127, v122, v126
	v_sub_f32_e32 v122, v122, v127
	v_sub_f32_e32 v124, v126, v124
	v_sub_f32_e32 v122, v122, v126
	v_add_f32_e32 v120, v120, v122
	v_sub_f32_e32 v122, v124, v125
	v_add_f32_e32 v120, v122, v120
	v_add_f32_e32 v122, v127, v120
	v_mul_f32_e32 v124, v121, v122
	v_mul_f32_e32 v125, v119, v124
	v_fma_f32 v119, v124, v119, -v125
	v_fmac_f32_e32 v119, v124, v117
	v_sub_f32_e32 v117, v127, v122
	v_add_f32_e32 v117, v120, v117
	v_add_f32_e32 v120, v125, v119
	v_sub_f32_e32 v126, v122, v120
	v_sub_f32_e32 v122, v122, v126
	v_sub_f32_e32 v125, v120, v125
	v_sub_f32_e32 v120, v122, v120
	v_add_f32_e32 v117, v117, v120
	v_sub_f32_e32 v119, v125, v119
	v_add_f32_e32 v117, v119, v117
	v_add_f32_e32 v119, v123, v124
	v_add_f32_e32 v117, v126, v117
	v_sub_f32_e32 v120, v119, v123
	v_mul_f32_e32 v117, v121, v117
	v_sub_f32_e32 v120, v124, v120
	v_add_f32_e32 v117, v120, v117
	v_mul_f32_e32 v123, 0x3f317218, v116
	v_add_f32_e32 v120, v119, v117
	v_fma_f32 v124, v116, s7, -v123
	v_mul_f32_e32 v121, v120, v120
	v_fmac_f32_e32 v124, 0xb102e308, v116
	v_sub_f32_e32 v116, v120, v119
	v_fmamk_f32 v122, v121, 0x3e9b6dac, v214
	v_sub_f32_e32 v116, v117, v116
	v_add_f32_e32 v117, v123, v124
	v_fmaak_f32 v122, v121, v122, 0x3f2aaada
	v_sub_f32_e32 v119, v117, v123
	v_ldexp_f32 v123, v120, 1
	v_mul_f32_e32 v120, v120, v121
	v_mul_f32_e32 v120, v120, v122
	v_add_f32_e32 v121, v123, v120
	v_sub_f32_e32 v122, v121, v123
	v_ldexp_f32 v116, v116, 1
	v_sub_f32_e32 v120, v120, v122
	v_add_f32_e32 v116, v116, v120
	v_add_f32_e32 v120, v121, v116
	v_sub_f32_e32 v121, v120, v121
	v_sub_f32_e32 v116, v116, v121
	v_add_f32_e32 v121, v117, v120
	v_sub_f32_e32 v122, v121, v117
	v_sub_f32_e32 v123, v121, v122
	v_sub_f32_e32 v119, v124, v119
	v_sub_f32_e32 v117, v117, v123
	v_sub_f32_e32 v120, v120, v122
	v_add_f32_e32 v117, v120, v117
	v_add_f32_e32 v120, v119, v116
;     __device__ __forceinline__ void operator()(const AccT& acc, const pg8::Unit& u, int wr, int wc, int fr, int fq) const {
;     ...
;                     } else if (wc == 1 && fq == 0) {
; #pragma unroll
;                         for (int n = 0; n < 2; ++n)
; #pragma unroll
;                             for (int j = 0; j < 4; ++j) {
;                                 const float x = acc[ai][0][m][n][j] * rs + bfg[4 * n + j];
;                                 lf[(4 * n + j) * MROWS + row] = fminf(x, 0.f) - log1pf(__expf(-fabsf(x)));
	v_sub_f32_e32 v122, v120, v119
	v_sub_f32_e32 v123, v120, v122
	v_sub_f32_e32 v119, v119, v123
	v_sub_f32_e32 v116, v116, v122
	v_add_f32_e32 v117, v120, v117
	v_add_f32_e32 v116, v116, v119
	v_add_f32_e32 v119, v121, v117
	v_sub_f32_e32 v120, v119, v121
	v_sub_f32_e32 v117, v117, v120
	v_add_f32_e32 v116, v116, v117
	v_add_f32_e32 v116, v119, v116
	v_cndmask_b32_e32 v116, v221, v116, vcc
	v_cmp_ngt_f32_e32 vcc, -1.0, v115
	s_nop 1
	v_cndmask_b32_e32 v116, v222, v116, vcc
	v_cmp_neq_f32_e32 vcc, -1.0, v115
	s_nop 1
	v_cndmask_b32_e32 v116, v219, v116, vcc
	v_cmp_lt_f32_e64 vcc, |v115|, s9
	s_nop 1
	v_cndmask_b32_e32 v115, v116, v115, vcc
	v_sub_f32_e32 v118, v118, v115
	global_store_dword v251, v118, s[52:53]
	v_add_f32_e32 v115, v249, v238
	v_min_f32_e32 v118, 0, v115
	v_mul_f32_e64 v115, |v115|, s3
	v_exp_f32_e32 v115, v115
	s_nop 0
	v_add_f32_e32 v119, 1.0, v115
	v_add_f32_e32 v116, -1.0, v119
	v_sub_f32_e32 v117, v116, v119
	v_add_f32_e32 v117, 1.0, v117
	v_sub_f32_e32 v116, v115, v116
	v_add_f32_e32 v120, v116, v117
	v_frexp_mant_f32_e32 v116, v119
	v_cmp_gt_f32_e32 vcc, s6, v116
	v_cvt_f64_f32_e32 v[116:117], v119
	v_frexp_exp_i32_f64_e32 v116, v[116:117]
	v_subbrev_co_u32_e32 v116, vcc, 0, v116, vcc
	v_sub_u32_e32 v117, 0, v116
	v_ldexp_f32 v119, v119, v117
	v_ldexp_f32 v117, v120, v117
	v_add_f32_e32 v120, -1.0, v119
	v_add_f32_e32 v121, 1.0, v120
	v_sub_f32_e32 v121, v119, v121
	v_add_f32_e32 v121, v117, v121
	v_add_f32_e32 v122, v120, v121
	v_sub_f32_e32 v120, v122, v120
	v_sub_f32_e32 v120, v121, v120
	v_add_f32_e32 v121, 1.0, v119
	v_add_f32_e32 v123, -1.0, v121
	v_sub_f32_e32 v119, v119, v123
	v_add_f32_e32 v117, v117, v119
	v_add_f32_e32 v119, v121, v117
	v_sub_f32_e32 v121, v119, v121
	v_sub_f32_e32 v117, v117, v121
	v_rcp_f32_e32 v121, v119
	v_cvt_f32_i32_e32 v116, v116
	v_cmp_neq_f32_e32 vcc, s8, v115
	v_mul_f32_e32 v123, v122, v121
	v_mul_f32_e32 v124, v119, v123
	v_fma_f32 v125, v123, v119, -v124
	v_fmac_f32_e32 v125, v123, v117
	v_add_f32_e32 v126, v124, v125
	v_sub_f32_e32 v127, v122, v126
	v_sub_f32_e32 v122, v122, v127
	v_sub_f32_e32 v124, v126, v124
	v_sub_f32_e32 v122, v122, v126
	v_add_f32_e32 v120, v120, v122
	v_sub_f32_e32 v122, v124, v125
	v_add_f32_e32 v120, v122, v120
	v_add_f32_e32 v122, v127, v120
	v_mul_f32_e32 v124, v121, v122
	v_mul_f32_e32 v125, v119, v124
	v_fma_f32 v119, v124, v119, -v125
	v_fmac_f32_e32 v119, v124, v117
	v_sub_f32_e32 v117, v127, v122
	v_add_f32_e32 v117, v120, v117
	v_add_f32_e32 v120, v125, v119
	v_sub_f32_e32 v126, v122, v120
	v_sub_f32_e32 v122, v122, v126
	v_sub_f32_e32 v125, v120, v125
	v_sub_f32_e32 v120, v122, v120
	v_add_f32_e32 v117, v117, v120
	v_sub_f32_e32 v119, v125, v119
	v_add_f32_e32 v117, v119, v117
	v_add_f32_e32 v119, v123, v124
	v_add_f32_e32 v117, v126, v117
	v_sub_f32_e32 v120, v119, v123
	v_mul_f32_e32 v117, v121, v117
	v_sub_f32_e32 v120, v124, v120
	v_add_f32_e32 v117, v120, v117
	v_mul_f32_e32 v123, 0x3f317218, v116
	v_add_f32_e32 v120, v119, v117
	v_fma_f32 v124, v116, s7, -v123
	v_mul_f32_e32 v121, v120, v120
	v_fmac_f32_e32 v124, 0xb102e308, v116
	v_sub_f32_e32 v116, v120, v119
	v_fmamk_f32 v122, v121, 0x3e9b6dac, v214
	v_sub_f32_e32 v116, v117, v116
	v_add_f32_e32 v117, v123, v124
	v_fmaak_f32 v122, v121, v122, 0x3f2aaada
	v_sub_f32_e32 v119, v117, v123
	v_ldexp_f32 v123, v120, 1
	v_mul_f32_e32 v120, v120, v121
	v_mul_f32_e32 v120, v120, v122
	v_add_f32_e32 v121, v123, v120
	v_sub_f32_e32 v122, v121, v123
	v_ldexp_f32 v116, v116, 1
	v_sub_f32_e32 v120, v120, v122
	v_add_f32_e32 v116, v116, v120
	v_add_f32_e32 v120, v121, v116
	v_sub_f32_e32 v121, v120, v121
	v_sub_f32_e32 v116, v116, v121
	v_add_f32_e32 v121, v117, v120
	v_sub_f32_e32 v122, v121, v117
	v_sub_f32_e32 v123, v121, v122
	v_sub_f32_e32 v119, v124, v119
	v_sub_f32_e32 v117, v117, v123
	v_sub_f32_e32 v120, v120, v122
	v_add_f32_e32 v117, v120, v117
	v_add_f32_e32 v120, v119, v116
	v_sub_f32_e32 v122, v120, v119
	v_sub_f32_e32 v123, v120, v122
	v_sub_f32_e32 v119, v119, v123
	v_sub_f32_e32 v116, v116, v122
	v_add_f32_e32 v117, v120, v117
	v_add_f32_e32 v116, v116, v119
	v_add_f32_e32 v119, v121, v117
	v_sub_f32_e32 v120, v119, v121
	v_sub_f32_e32 v117, v117, v120
	v_add_f32_e32 v116, v116, v117
	v_add_f32_e32 v116, v119, v116
	v_cndmask_b32_e32 v116, v221, v116, vcc
	v_cmp_ngt_f32_e32 vcc, -1.0, v115
	s_nop 1
	v_cndmask_b32_e32 v116, v222, v116, vcc
	v_cmp_neq_f32_e32 vcc, -1.0, v115
	s_nop 1
	v_cndmask_b32_e32 v116, v219, v116, vcc
	v_cmp_lt_f32_e64 vcc, |v115|, s9
	s_nop 1
	v_cndmask_b32_e32 v115, v116, v115, vcc
	v_sub_f32_e32 v118, v118, v115
	global_store_dword v246, v118, s[52:53]

;     __device__ __forceinline__ void operator()(const AccT& acc, const pg8::Unit& u, int wr, int wc, int fr, int fq) const {
;     ...
;         for (int ai = 0; ai < 2; ++ai)
; #pragma unroll
;             for (int m = 0; m < 4; ++m) {
;                 const int row = row0 + ai * 128 + m * 16;
;                 const float rs = 1.0f;
;                 if (u.pn < 20) {
;     ...
;                     } else if (wc == 1 && fq == 0) {
; #pragma unroll
;                         for (int n = 0; n < 2; ++n)
; #pragma unroll
;                             for (int j = 0; j < 4; ++j) {
;                                 const float x = acc[ai][0][m][n][j] * rs + bfg[4 * n + j];
;                                 lf[(4 * n + j) * MROWS + row] = fminf(x, 0.f) - log1pf(__expf(-fabsf(x)));
.LBB0_972:
	v_or_b32_e32 v98, 32, v150
	s_and_b64 vcc, exec, s[44:45]
	s_mov_b64 s[8:9], -1
	s_cbranch_vccnz .LBB0_980
	s_and_b64 vcc, exec, s[42:43]
	s_cbranch_vccnz .LBB0_977
	s_mov_b64 s[70:71], exec
	s_and_b64 s[100:101], exec, s[58:59]
	s_cbranch_scc0 .LBB0_976
	s_mov_b32 s3, 0xbfb8aa3b
	s_mov_b32 s6, 0x3f2aaaab
	s_mov_b32 s7, 0x3f317218
	s_mov_b32 s8, 0x7f800000
	s_mov_b32 s9, 0x33800000
	s_mov_b32 s2, 0x8000
	s_waitcnt lgkmcnt(0)
	ds_bpermute_b32 v94, v250, v94
	ds_bpermute_b32 v95, v250, v95
	ds_bpermute_b32 v96, v250, v96
	ds_bpermute_b32 v97, v250, v97
	ds_bpermute_b32 v90, v250, v90
	ds_bpermute_b32 v91, v250, v91
	ds_bpermute_b32 v92, v250, v92
	ds_bpermute_b32 v93, v250, v93
	s_mov_b32 s100, 0x10800
	v_lshlrev_b32_e32 v251, 2, v98
	s_waitcnt lgkmcnt(0)
	v_mov_b32_e32 v248, v94
	v_mov_b32_e32 v249, v95
	v_cmp_eq_u32_e32 vcc, 1, v239
	s_nop 1
	v_cndmask_b32_e32 v248, v248, v96, vcc
	v_cndmask_b32_e32 v249, v249, v97, vcc
	v_cmp_eq_u32_e32 vcc, 2, v239
	s_nop 1
	v_cndmask_b32_e32 v248, v248, v90, vcc
	v_cndmask_b32_e32 v249, v249, v91, vcc
	v_cmp_eq_u32_e32 vcc, 3, v239
	s_nop 1
	v_cndmask_b32_e32 v248, v248, v92, vcc
	v_cndmask_b32_e32 v249, v249, v93, vcc
	v_mad_u32_u24 v251, v239, s100, v251
	v_add_u32_e32 v246, 0x8400, v251
	v_add_f32_e32 v99, v248, v223
	v_min_f32_e32 v102, 0, v99
	v_mul_f32_e64 v99, |v99|, s3
	v_exp_f32_e32 v99, v99
	s_nop 0
	v_add_f32_e32 v103, 1.0, v99
	v_add_f32_e32 v100, -1.0, v103
	v_sub_f32_e32 v101, v100, v103
	v_add_f32_e32 v101, 1.0, v101
	v_sub_f32_e32 v100, v99, v100
	v_add_f32_e32 v104, v100, v101
	v_frexp_mant_f32_e32 v100, v103
	v_cmp_gt_f32_e32 vcc, s6, v100
	v_cvt_f64_f32_e32 v[100:101], v103
	v_frexp_exp_i32_f64_e32 v100, v[100:101]
	v_subbrev_co_u32_e32 v100, vcc, 0, v100, vcc
	v_sub_u32_e32 v101, 0, v100
	v_ldexp_f32 v103, v103, v101
	v_ldexp_f32 v101, v104, v101
	v_add_f32_e32 v104, -1.0, v103
	v_add_f32_e32 v105, 1.0, v104
	v_sub_f32_e32 v105, v103, v105
	v_add_f32_e32 v105, v101, v105
	v_add_f32_e32 v106, v104, v105
	v_sub_f32_e32 v104, v106, v104
	v_sub_f32_e32 v104, v105, v104
	v_add_f32_e32 v105, 1.0, v103
	v_add_f32_e32 v107, -1.0, v105
	v_sub_f32_e32 v103, v103, v107
	v_add_f32_e32 v101, v101, v103
	v_add_f32_e32 v103, v105, v101
	v_sub_f32_e32 v105, v103, v105
	v_sub_f32_e32 v101, v101, v105
	v_rcp_f32_e32 v105, v103
	v_cvt_f32_i32_e32 v100, v100
	v_cmp_neq_f32_e32 vcc, s8, v99
	v_mul_f32_e32 v107, v106, v105
	v_mul_f32_e32 v108, v103, v107
	v_fma_f32 v109, v107, v103, -v108
	v_fmac_f32_e32 v109, v107, v101
	v_add_f32_e32 v110, v108, v109
	v_sub_f32_e32 v111, v106, v110
	v_sub_f32_e32 v106, v106, v111
	v_sub_f32_e32 v108, v110, v108
	v_sub_f32_e32 v106, v106, v110
	v_add_f32_e32 v104, v104, v106
	v_sub_f32_e32 v106, v108, v109
	v_add_f32_e32 v104, v106, v104
	v_add_f32_e32 v106, v111, v104
	v_mul_f32_e32 v108, v105, v106
	v_mul_f32_e32 v109, v103, v108
	v_fma_f32 v103, v108, v103, -v109
	v_fmac_f32_e32 v103, v108, v101
	v_sub_f32_e32 v101, v111, v106
	v_add_f32_e32 v101, v104, v101
	v_add_f32_e32 v104, v109, v103
	v_sub_f32_e32 v110, v106, v104
	v_sub_f32_e32 v106, v106, v110
	v_sub_f32_e32 v109, v104, v109
	v_sub_f32_e32 v104, v106, v104
	v_add_f32_e32 v101, v101, v104
	v_sub_f32_e32 v103, v109, v103
	v_add_f32_e32 v101, v103, v101
	v_add_f32_e32 v103, v107, v108
	v_add_f32_e32 v101, v110, v101
	v_sub_f32_e32 v104, v103, v107
	v_mul_f32_e32 v101, v105, v101
	v_sub_f32_e32 v104, v108, v104
	v_add_f32_e32 v101, v104, v101
	v_mul_f32_e32 v107, 0x3f317218, v100
	v_add_f32_e32 v104, v103, v101
	v_fma_f32 v108, v100, s7, -v107
	v_mul_f32_e32 v105, v104, v104
	v_fmac_f32_e32 v108, 0xb102e308, v100
	v_sub_f32_e32 v100, v104, v103
	v_fmamk_f32 v106, v105, 0x3e9b6dac, v214
	v_sub_f32_e32 v100, v101, v100
	v_add_f32_e32 v101, v107, v108
	v_fmaak_f32 v106, v105, v106, 0x3f2aaada
	v_sub_f32_e32 v103, v101, v107
	v_ldexp_f32 v107, v104, 1
	v_mul_f32_e32 v104, v104, v105
	v_mul_f32_e32 v104, v104, v106
	v_add_f32_e32 v105, v107, v104
	v_sub_f32_e32 v106, v105, v107
	v_ldexp_f32 v100, v100, 1
	v_sub_f32_e32 v104, v104, v106
	v_add_f32_e32 v100, v100, v104
	v_add_f32_e32 v104, v105, v100
	v_sub_f32_e32 v105, v104, v105
	v_sub_f32_e32 v100, v100, v105
	v_add_f32_e32 v105, v101, v104
	v_sub_f32_e32 v106, v105, v101
	v_sub_f32_e32 v107, v105, v106
	v_sub_f32_e32 v103, v108, v103
	v_sub_f32_e32 v101, v101, v107
	v_sub_f32_e32 v104, v104, v106
	v_add_f32_e32 v101, v104, v101
	v_add_f32_e32 v104, v103, v100
	v_sub_f32_e32 v106, v104, v103
	v_sub_f32_e32 v107, v104, v106
	v_sub_f32_e32 v103, v103, v107
;     __device__ __forceinline__ void operator()(const AccT& acc, const pg8::Unit& u, int wr, int wc, int fr, int fq) const {
;     ...
;                     } else if (wc == 1 && fq == 0) {
; #pragma unroll
;                         for (int n = 0; n < 2; ++n)
; #pragma unroll
;                             for (int j = 0; j < 4; ++j) {
;                                 const float x = acc[ai][0][m][n][j] * rs + bfg[4 * n + j];
;                                 lf[(4 * n + j) * MROWS + row] = fminf(x, 0.f) - log1pf(__expf(-fabsf(x)));
	v_sub_f32_e32 v100, v100, v106
	v_add_f32_e32 v101, v104, v101
	v_add_f32_e32 v100, v100, v103
	v_add_f32_e32 v103, v105, v101
	v_sub_f32_e32 v104, v103, v105
	v_sub_f32_e32 v101, v101, v104
	v_add_f32_e32 v100, v100, v101
	v_add_f32_e32 v100, v103, v100
	v_cndmask_b32_e32 v100, v221, v100, vcc
	v_cmp_ngt_f32_e32 vcc, -1.0, v99
	s_nop 1
	v_cndmask_b32_e32 v100, v222, v100, vcc
	v_cmp_neq_f32_e32 vcc, -1.0, v99
	s_nop 1
	v_cndmask_b32_e32 v100, v219, v100, vcc
	v_cmp_lt_f32_e64 vcc, |v99|, s9
	s_nop 1
	v_cndmask_b32_e32 v99, v100, v99, vcc
	v_sub_f32_e32 v102, v102, v99
	global_store_dword v251, v102, s[52:53]
	v_add_f32_e32 v99, v249, v238
	v_min_f32_e32 v102, 0, v99
	v_mul_f32_e64 v99, |v99|, s3
	v_exp_f32_e32 v99, v99
	s_nop 0
	v_add_f32_e32 v103, 1.0, v99
	v_add_f32_e32 v100, -1.0, v103
	v_sub_f32_e32 v101, v100, v103
	v_add_f32_e32 v101, 1.0, v101
	v_sub_f32_e32 v100, v99, v100
	v_add_f32_e32 v104, v100, v101
	v_frexp_mant_f32_e32 v100, v103
	v_cmp_gt_f32_e32 vcc, s6, v100
	v_cvt_f64_f32_e32 v[100:101], v103
	v_frexp_exp_i32_f64_e32 v100, v[100:101]
	v_subbrev_co_u32_e32 v100, vcc, 0, v100, vcc
	v_sub_u32_e32 v101, 0, v100
	v_ldexp_f32 v103, v103, v101
	v_ldexp_f32 v101, v104, v101
	v_add_f32_e32 v104, -1.0, v103
	v_add_f32_e32 v105, 1.0, v104
	v_sub_f32_e32 v105, v103, v105
	v_add_f32_e32 v105, v101, v105
	v_add_f32_e32 v106, v104, v105
	v_sub_f32_e32 v104, v106, v104
	v_sub_f32_e32 v104, v105, v104
	v_add_f32_e32 v105, 1.0, v103
	v_add_f32_e32 v107, -1.0, v105
	v_sub_f32_e32 v103, v103, v107
	v_add_f32_e32 v101, v101, v103
	v_add_f32_e32 v103, v105, v101
	v_sub_f32_e32 v105, v103, v105
	v_sub_f32_e32 v101, v101, v105
	v_rcp_f32_e32 v105, v103
	v_cvt_f32_i32_e32 v100, v100
	v_cmp_neq_f32_e32 vcc, s8, v99
	v_mul_f32_e32 v107, v106, v105
	v_mul_f32_e32 v108, v103, v107
	v_fma_f32 v109, v107, v103, -v108
	v_fmac_f32_e32 v109, v107, v101
	v_add_f32_e32 v110, v108, v109
	v_sub_f32_e32 v111, v106, v110
	v_sub_f32_e32 v106, v106, v111
	v_sub_f32_e32 v108, v110, v108
	v_sub_f32_e32 v106, v106, v110
	v_add_f32_e32 v104, v104, v106
	v_sub_f32_e32 v106, v108, v109
	v_add_f32_e32 v104, v106, v104
	v_add_f32_e32 v106, v111, v104
	v_mul_f32_e32 v108, v105, v106
	v_mul_f32_e32 v109, v103, v108
	v_fma_f32 v103, v108, v103, -v109
	v_fmac_f32_e32 v103, v108, v101
	v_sub_f32_e32 v101, v111, v106
	v_add_f32_e32 v101, v104, v101
	v_add_f32_e32 v104, v109, v103
	v_sub_f32_e32 v110, v106, v104
	v_sub_f32_e32 v106, v106, v110
	v_sub_f32_e32 v109, v104, v109
	v_sub_f32_e32 v104, v106, v104
	v_add_f32_e32 v101, v101, v104
	v_sub_f32_e32 v103, v109, v103
	v_add_f32_e32 v101, v103, v101
	v_add_f32_e32 v103, v107, v108
	v_add_f32_e32 v101, v110, v101
	v_sub_f32_e32 v104, v103, v107
	v_mul_f32_e32 v101, v105, v101
	v_sub_f32_e32 v104, v108, v104
	v_add_f32_e32 v101, v104, v101
	v_mul_f32_e32 v107, 0x3f317218, v100
	v_add_f32_e32 v104, v103, v101
	v_fma_f32 v108, v100, s7, -v107
	v_mul_f32_e32 v105, v104, v104
	v_fmac_f32_e32 v108, 0xb102e308, v100
	v_sub_f32_e32 v100, v104, v103
	v_fmamk_f32 v106, v105, 0x3e9b6dac, v214
	v_sub_f32_e32 v100, v101, v100
	v_add_f32_e32 v101, v107, v108
	v_fmaak_f32 v106, v105, v106, 0x3f2aaada
	v_sub_f32_e32 v103, v101, v107
	v_ldexp_f32 v107, v104, 1
	v_mul_f32_e32 v104, v104, v105
	v_mul_f32_e32 v104, v104, v106
	v_add_f32_e32 v105, v107, v104
	v_sub_f32_e32 v106, v105, v107
	v_ldexp_f32 v100, v100, 1
	v_sub_f32_e32 v104, v104, v106
	v_add_f32_e32 v100, v100, v104
	v_add_f32_e32 v104, v105, v100
	v_sub_f32_e32 v105, v104, v105
	v_sub_f32_e32 v100, v100, v105
	v_add_f32_e32 v105, v101, v104
	v_sub_f32_e32 v106, v105, v101
	v_sub_f32_e32 v107, v105, v106
	v_sub_f32_e32 v103, v108, v103
	v_sub_f32_e32 v101, v101, v107
	v_sub_f32_e32 v104, v104, v106
	v_add_f32_e32 v101, v104, v101
	v_add_f32_e32 v104, v103, v100
	v_sub_f32_e32 v106, v104, v103
	v_sub_f32_e32 v107, v104, v106
	v_sub_f32_e32 v103, v103, v107
	v_sub_f32_e32 v100, v100, v106
	v_add_f32_e32 v101, v104, v101
	v_add_f32_e32 v100, v100, v103
	v_add_f32_e32 v103, v105, v101
	v_sub_f32_e32 v104, v103, v105
	v_sub_f32_e32 v101, v101, v104
	v_add_f32_e32 v100, v100, v101
	v_add_f32_e32 v100, v103, v100
	v_cndmask_b32_e32 v100, v221, v100, vcc
	v_cmp_ngt_f32_e32 vcc, -1.0, v99
	s_nop 1
	v_cndmask_b32_e32 v100, v222, v100, vcc
	v_cmp_neq_f32_e32 vcc, -1.0, v99
	s_nop 1
	v_cndmask_b32_e32 v100, v219, v100, vcc
	v_cmp_lt_f32_e64 vcc, |v99|, s9
	s_nop 1
	v_cndmask_b32_e32 v99, v100, v99, vcc
	v_sub_f32_e32 v102, v102, v99
	global_store_dword v246, v102, s[52:53]

;     __device__ __forceinline__ void operator()(const AccT& acc, const pg8::Unit& u, int wr, int wc, int fr, int fq) const {
;     ...
;         for (int ai = 0; ai < 2; ++ai)
; #pragma unroll
;             for (int m = 0; m < 4; ++m) {
;                 const int row = row0 + ai * 128 + m * 16;
;                 const float rs = 1.0f;
;                 if (u.pn < 20) {
;     ...
;                     } else if (wc == 1 && fq == 0) {
; #pragma unroll
;                         for (int n = 0; n < 2; ++n)
; #pragma unroll
;                             for (int j = 0; j < 4; ++j) {
;                                 const float x = acc[ai][0][m][n][j] * rs + bfg[4 * n + j];
;                                 lf[(4 * n + j) * MROWS + row] = fminf(x, 0.f) - log1pf(__expf(-fabsf(x)));
.LBB0_985:
	v_or_b32_e32 v82, 48, v150
	s_and_b64 vcc, exec, s[44:45]
	s_mov_b64 s[8:9], -1
	s_cbranch_vccnz .LBB0_993
	s_and_b64 vcc, exec, s[42:43]
	s_cbranch_vccnz .LBB0_990
	s_mov_b64 s[70:71], exec
	s_and_b64 s[100:101], exec, s[58:59]
	s_cbranch_scc0 .LBB0_989
	s_mov_b32 s3, 0xbfb8aa3b
	s_mov_b32 s6, 0x3f2aaaab
	s_mov_b32 s7, 0x3f317218
	s_mov_b32 s8, 0x7f800000
	s_mov_b32 s9, 0x33800000
	s_mov_b32 s2, 0x8000
	s_waitcnt lgkmcnt(0)
	ds_bpermute_b32 v78, v250, v78
	ds_bpermute_b32 v79, v250, v79
	ds_bpermute_b32 v80, v250, v80
	ds_bpermute_b32 v81, v250, v81
	ds_bpermute_b32 v74, v250, v74
	ds_bpermute_b32 v75, v250, v75
	ds_bpermute_b32 v76, v250, v76
	ds_bpermute_b32 v77, v250, v77
	s_mov_b32 s100, 0x10800
	v_lshlrev_b32_e32 v251, 2, v82
	s_waitcnt lgkmcnt(0)
	v_mov_b32_e32 v248, v78
	v_mov_b32_e32 v249, v79
	v_cmp_eq_u32_e32 vcc, 1, v239
	s_nop 1
	v_cndmask_b32_e32 v248, v248, v80, vcc
	v_cndmask_b32_e32 v249, v249, v81, vcc
	v_cmp_eq_u32_e32 vcc, 2, v239
	s_nop 1
	v_cndmask_b32_e32 v248, v248, v74, vcc
	v_cndmask_b32_e32 v249, v249, v75, vcc
	v_cmp_eq_u32_e32 vcc, 3, v239
	s_nop 1
	v_cndmask_b32_e32 v248, v248, v76, vcc
	v_cndmask_b32_e32 v249, v249, v77, vcc
	v_mad_u32_u24 v251, v239, s100, v251
	v_add_u32_e32 v246, 0x8400, v251
	v_add_f32_e32 v83, v248, v223
	v_min_f32_e32 v86, 0, v83
	v_mul_f32_e64 v83, |v83|, s3
	v_exp_f32_e32 v83, v83
	s_nop 0
	v_add_f32_e32 v87, 1.0, v83
	v_add_f32_e32 v84, -1.0, v87
	v_sub_f32_e32 v85, v84, v87
	v_add_f32_e32 v85, 1.0, v85
	v_sub_f32_e32 v84, v83, v84
	v_add_f32_e32 v88, v84, v85
	v_frexp_mant_f32_e32 v84, v87
	v_cmp_gt_f32_e32 vcc, s6, v84
	v_cvt_f64_f32_e32 v[84:85], v87
	v_frexp_exp_i32_f64_e32 v84, v[84:85]
	v_subbrev_co_u32_e32 v84, vcc, 0, v84, vcc
	v_sub_u32_e32 v85, 0, v84
	v_ldexp_f32 v87, v87, v85
	v_ldexp_f32 v85, v88, v85
	v_add_f32_e32 v88, -1.0, v87
	v_add_f32_e32 v89, 1.0, v88
	v_sub_f32_e32 v89, v87, v89
	v_add_f32_e32 v89, v85, v89
	v_add_f32_e32 v90, v88, v89
	v_sub_f32_e32 v88, v90, v88
	v_sub_f32_e32 v88, v89, v88
	v_add_f32_e32 v89, 1.0, v87
	v_add_f32_e32 v91, -1.0, v89
	v_sub_f32_e32 v87, v87, v91
	v_add_f32_e32 v85, v85, v87
	v_add_f32_e32 v87, v89, v85
	v_sub_f32_e32 v89, v87, v89
	v_sub_f32_e32 v85, v85, v89
	v_rcp_f32_e32 v89, v87
	v_cvt_f32_i32_e32 v84, v84
	v_cmp_neq_f32_e32 vcc, s8, v83
	v_mul_f32_e32 v91, v90, v89
	v_mul_f32_e32 v92, v87, v91
	v_fma_f32 v93, v91, v87, -v92
	v_fmac_f32_e32 v93, v91, v85
	v_add_f32_e32 v94, v92, v93
	v_sub_f32_e32 v95, v90, v94
	v_sub_f32_e32 v90, v90, v95
	v_sub_f32_e32 v92, v94, v92
	v_sub_f32_e32 v90, v90, v94
	v_add_f32_e32 v88, v88, v90
	v_sub_f32_e32 v90, v92, v93
	v_add_f32_e32 v88, v90, v88
	v_add_f32_e32 v90, v95, v88
	v_mul_f32_e32 v92, v89, v90
	v_mul_f32_e32 v93, v87, v92
	v_fma_f32 v87, v92, v87, -v93
	v_fmac_f32_e32 v87, v92, v85
	v_sub_f32_e32 v85, v95, v90
	v_add_f32_e32 v85, v88, v85
	v_add_f32_e32 v88, v93, v87
	v_sub_f32_e32 v94, v90, v88
	v_sub_f32_e32 v90, v90, v94
	v_sub_f32_e32 v93, v88, v93
	v_sub_f32_e32 v88, v90, v88
	v_add_f32_e32 v85, v85, v88
	v_sub_f32_e32 v87, v93, v87
	v_add_f32_e32 v85, v87, v85
	v_add_f32_e32 v87, v91, v92
	v_add_f32_e32 v85, v94, v85
	v_sub_f32_e32 v88, v87, v91
	v_mul_f32_e32 v85, v89, v85
	v_sub_f32_e32 v88, v92, v88
	v_add_f32_e32 v85, v88, v85
	v_mul_f32_e32 v91, 0x3f317218, v84
	v_add_f32_e32 v88, v87, v85
	v_fma_f32 v92, v84, s7, -v91
	v_mul_f32_e32 v89, v88, v88
	v_fmac_f32_e32 v92, 0xb102e308, v84
	v_sub_f32_e32 v84, v88, v87
	v_fmamk_f32 v90, v89, 0x3e9b6dac, v214
	v_sub_f32_e32 v84, v85, v84
	v_add_f32_e32 v85, v91, v92
	v_fmaak_f32 v90, v89, v90, 0x3f2aaada
	v_sub_f32_e32 v87, v85, v91
	v_ldexp_f32 v91, v88, 1
	v_mul_f32_e32 v88, v88, v89
	v_mul_f32_e32 v88, v88, v90
	v_add_f32_e32 v89, v91, v88
	v_sub_f32_e32 v90, v89, v91
	v_ldexp_f32 v84, v84, 1
	v_sub_f32_e32 v88, v88, v90
	v_add_f32_e32 v84, v84, v88
	v_add_f32_e32 v88, v89, v84
	v_sub_f32_e32 v89, v88, v89
	v_sub_f32_e32 v84, v84, v89
	v_add_f32_e32 v89, v85, v88
	v_sub_f32_e32 v90, v89, v85
	v_sub_f32_e32 v91, v89, v90
	v_sub_f32_e32 v87, v92, v87
	v_sub_f32_e32 v85, v85, v91
	v_sub_f32_e32 v88, v88, v90
	v_add_f32_e32 v85, v88, v85
	v_add_f32_e32 v88, v87, v84
	v_sub_f32_e32 v90, v88, v87
;     __device__ __forceinline__ void operator()(const AccT& acc, const pg8::Unit& u, int wr, int wc, int fr, int fq) const {
;     ...
;                     } else if (wc == 1 && fq == 0) {
; #pragma unroll
;                         for (int n = 0; n < 2; ++n)
; #pragma unroll
;                             for (int j = 0; j < 4; ++j) {
;                                 const float x = acc[ai][0][m][n][j] * rs + bfg[4 * n + j];
;                                 lf[(4 * n + j) * MROWS + row] = fminf(x, 0.f) - log1pf(__expf(-fabsf(x)));
	v_sub_f32_e32 v91, v88, v90
	v_sub_f32_e32 v87, v87, v91
	v_sub_f32_e32 v84, v84, v90
	v_add_f32_e32 v85, v88, v85
	v_add_f32_e32 v84, v84, v87
	v_add_f32_e32 v87, v89, v85
	v_sub_f32_e32 v88, v87, v89
	v_sub_f32_e32 v85, v85, v88
	v_add_f32_e32 v84, v84, v85
	v_add_f32_e32 v84, v87, v84
	v_cndmask_b32_e32 v84, v221, v84, vcc
	v_cmp_ngt_f32_e32 vcc, -1.0, v83
	s_nop 1
	v_cndmask_b32_e32 v84, v222, v84, vcc
	v_cmp_neq_f32_e32 vcc, -1.0, v83
	s_nop 1
	v_cndmask_b32_e32 v84, v219, v84, vcc
	v_cmp_lt_f32_e64 vcc, |v83|, s9
	s_nop 1
	v_cndmask_b32_e32 v83, v84, v83, vcc
	v_sub_f32_e32 v86, v86, v83
	global_store_dword v251, v86, s[52:53]
	v_add_f32_e32 v83, v249, v238
	v_min_f32_e32 v86, 0, v83
	v_mul_f32_e64 v83, |v83|, s3
	v_exp_f32_e32 v83, v83
	s_nop 0
	v_add_f32_e32 v87, 1.0, v83
	v_add_f32_e32 v84, -1.0, v87
	v_sub_f32_e32 v85, v84, v87
	v_add_f32_e32 v85, 1.0, v85
	v_sub_f32_e32 v84, v83, v84
	v_add_f32_e32 v88, v84, v85
	v_frexp_mant_f32_e32 v84, v87
	v_cmp_gt_f32_e32 vcc, s6, v84
	v_cvt_f64_f32_e32 v[84:85], v87
	v_frexp_exp_i32_f64_e32 v84, v[84:85]
	v_subbrev_co_u32_e32 v84, vcc, 0, v84, vcc
	v_sub_u32_e32 v85, 0, v84
	v_ldexp_f32 v87, v87, v85
	v_ldexp_f32 v85, v88, v85
	v_add_f32_e32 v88, -1.0, v87
	v_add_f32_e32 v89, 1.0, v88
	v_sub_f32_e32 v89, v87, v89
	v_add_f32_e32 v89, v85, v89
	v_add_f32_e32 v90, v88, v89
	v_sub_f32_e32 v88, v90, v88
	v_sub_f32_e32 v88, v89, v88
	v_add_f32_e32 v89, 1.0, v87
	v_add_f32_e32 v91, -1.0, v89
	v_sub_f32_e32 v87, v87, v91
	v_add_f32_e32 v85, v85, v87
	v_add_f32_e32 v87, v89, v85
	v_sub_f32_e32 v89, v87, v89
	v_sub_f32_e32 v85, v85, v89
	v_rcp_f32_e32 v89, v87
	v_cvt_f32_i32_e32 v84, v84
	v_cmp_neq_f32_e32 vcc, s8, v83
	v_mul_f32_e32 v91, v90, v89
	v_mul_f32_e32 v92, v87, v91
	v_fma_f32 v93, v91, v87, -v92
	v_fmac_f32_e32 v93, v91, v85
	v_add_f32_e32 v94, v92, v93
	v_sub_f32_e32 v95, v90, v94
	v_sub_f32_e32 v90, v90, v95
	v_sub_f32_e32 v92, v94, v92
	v_sub_f32_e32 v90, v90, v94
	v_add_f32_e32 v88, v88, v90
	v_sub_f32_e32 v90, v92, v93
	v_add_f32_e32 v88, v90, v88
	v_add_f32_e32 v90, v95, v88
	v_mul_f32_e32 v92, v89, v90
	v_mul_f32_e32 v93, v87, v92
	v_fma_f32 v87, v92, v87, -v93
	v_fmac_f32_e32 v87, v92, v85
	v_sub_f32_e32 v85, v95, v90
	v_add_f32_e32 v85, v88, v85
	v_add_f32_e32 v88, v93, v87
	v_sub_f32_e32 v94, v90, v88
	v_sub_f32_e32 v90, v90, v94
	v_sub_f32_e32 v93, v88, v93
	v_sub_f32_e32 v88, v90, v88
	v_add_f32_e32 v85, v85, v88
	v_sub_f32_e32 v87, v93, v87
	v_add_f32_e32 v85, v87, v85
	v_add_f32_e32 v87, v91, v92
	v_add_f32_e32 v85, v94, v85
	v_sub_f32_e32 v88, v87, v91
	v_mul_f32_e32 v85, v89, v85
	v_sub_f32_e32 v88, v92, v88
	v_add_f32_e32 v85, v88, v85
	v_mul_f32_e32 v91, 0x3f317218, v84
	v_add_f32_e32 v88, v87, v85
	v_fma_f32 v92, v84, s7, -v91
	v_mul_f32_e32 v89, v88, v88
	v_fmac_f32_e32 v92, 0xb102e308, v84
	v_sub_f32_e32 v84, v88, v87
	v_fmamk_f32 v90, v89, 0x3e9b6dac, v214
	v_sub_f32_e32 v84, v85, v84
	v_add_f32_e32 v85, v91, v92
	v_fmaak_f32 v90, v89, v90, 0x3f2aaada
	v_sub_f32_e32 v87, v85, v91
	v_ldexp_f32 v91, v88, 1
	v_mul_f32_e32 v88, v88, v89
	v_mul_f32_e32 v88, v88, v90
	v_add_f32_e32 v89, v91, v88
	v_sub_f32_e32 v90, v89, v91
	v_ldexp_f32 v84, v84, 1
	v_sub_f32_e32 v88, v88, v90
	v_add_f32_e32 v84, v84, v88
	v_add_f32_e32 v88, v89, v84
	v_sub_f32_e32 v89, v88, v89
	v_sub_f32_e32 v84, v84, v89
	v_add_f32_e32 v89, v85, v88
	v_sub_f32_e32 v90, v89, v85
	v_sub_f32_e32 v91, v89, v90
	v_sub_f32_e32 v87, v92, v87
	v_sub_f32_e32 v85, v85, v91
	v_sub_f32_e32 v88, v88, v90
	v_add_f32_e32 v85, v88, v85
	v_add_f32_e32 v88, v87, v84
	v_sub_f32_e32 v90, v88, v87
	v_sub_f32_e32 v91, v88, v90
	v_sub_f32_e32 v87, v87, v91
	v_sub_f32_e32 v84, v84, v90
	v_add_f32_e32 v85, v88, v85
	v_add_f32_e32 v84, v84, v87
	v_add_f32_e32 v87, v89, v85
	v_sub_f32_e32 v88, v87, v89
	v_sub_f32_e32 v85, v85, v88
	v_add_f32_e32 v84, v84, v85
	v_add_f32_e32 v84, v87, v84
	v_cndmask_b32_e32 v84, v221, v84, vcc
	v_cmp_ngt_f32_e32 vcc, -1.0, v83
	s_nop 1
	v_cndmask_b32_e32 v84, v222, v84, vcc
	v_cmp_neq_f32_e32 vcc, -1.0, v83
	s_nop 1
	v_cndmask_b32_e32 v84, v219, v84, vcc
	v_cmp_lt_f32_e64 vcc, |v83|, s9
	s_nop 1
	v_cndmask_b32_e32 v83, v84, v83, vcc
	v_sub_f32_e32 v86, v86, v83
	global_store_dword v246, v86, s[52:53]

;     __device__ __forceinline__ void operator()(const AccT& acc, const pg8::Unit& u, int wr, int wc, int fr, int fq) const {
;     ...
;         for (int ai = 0; ai < 2; ++ai)
; #pragma unroll
;             for (int m = 0; m < 4; ++m) {
;                 const int row = row0 + ai * 128 + m * 16;
;                 const float rs = 1.0f;
;                 if (u.pn < 20) {
;     ...
;                     } else if (wc == 1 && fq == 0) {
; #pragma unroll
;                         for (int n = 0; n < 2; ++n)
; #pragma unroll
;                             for (int j = 0; j < 4; ++j) {
;                                 const float x = acc[ai][0][m][n][j] * rs + bfg[4 * n + j];
;                                 lf[(4 * n + j) * MROWS + row] = fminf(x, 0.f) - log1pf(__expf(-fabsf(x)));
.LBB0_998:
	v_add_u32_e32 v66, 0x80, v150
	s_and_b64 vcc, exec, s[44:45]
	s_mov_b64 s[8:9], -1
	s_cbranch_vccnz .LBB0_1006
	s_and_b64 vcc, exec, s[42:43]
	s_cbranch_vccnz .LBB0_1003
	s_mov_b64 s[70:71], exec
	s_and_b64 s[100:101], exec, s[58:59]
	s_cbranch_scc0 .LBB0_1002
	s_mov_b32 s3, 0xbfb8aa3b
	s_mov_b32 s6, 0x3f2aaaab
	s_mov_b32 s7, 0x3f317218
	s_mov_b32 s8, 0x7f800000
	s_mov_b32 s9, 0x33800000
	s_mov_b32 s2, 0x8000
	s_waitcnt lgkmcnt(0)
	ds_bpermute_b32 v62, v250, v62
	ds_bpermute_b32 v63, v250, v63
	ds_bpermute_b32 v64, v250, v64
	ds_bpermute_b32 v65, v250, v65
	ds_bpermute_b32 v58, v250, v58
	ds_bpermute_b32 v59, v250, v59
	ds_bpermute_b32 v60, v250, v60
	ds_bpermute_b32 v61, v250, v61
	s_mov_b32 s100, 0x10800
	v_lshlrev_b32_e32 v251, 2, v66
	s_waitcnt lgkmcnt(0)
	v_mov_b32_e32 v248, v62
	v_mov_b32_e32 v249, v63
	v_cmp_eq_u32_e32 vcc, 1, v239
	s_nop 1
	v_cndmask_b32_e32 v248, v248, v64, vcc
	v_cndmask_b32_e32 v249, v249, v65, vcc
	v_cmp_eq_u32_e32 vcc, 2, v239
	s_nop 1
	v_cndmask_b32_e32 v248, v248, v58, vcc
	v_cndmask_b32_e32 v249, v249, v59, vcc
	v_cmp_eq_u32_e32 vcc, 3, v239
	s_nop 1
	v_cndmask_b32_e32 v248, v248, v60, vcc
	v_cndmask_b32_e32 v249, v249, v61, vcc
	v_mad_u32_u24 v251, v239, s100, v251
	v_add_u32_e32 v246, 0x8400, v251
	v_add_f32_e32 v67, v248, v223
	v_min_f32_e32 v70, 0, v67
	v_mul_f32_e64 v67, |v67|, s3
	v_exp_f32_e32 v67, v67
	s_nop 0
	v_add_f32_e32 v71, 1.0, v67
	v_add_f32_e32 v68, -1.0, v71
	v_sub_f32_e32 v69, v68, v71
	v_add_f32_e32 v69, 1.0, v69
	v_sub_f32_e32 v68, v67, v68
	v_add_f32_e32 v72, v68, v69
	v_frexp_mant_f32_e32 v68, v71
	v_cmp_gt_f32_e32 vcc, s6, v68
	v_cvt_f64_f32_e32 v[68:69], v71
	v_frexp_exp_i32_f64_e32 v68, v[68:69]
	v_subbrev_co_u32_e32 v68, vcc, 0, v68, vcc
	v_sub_u32_e32 v69, 0, v68
	v_ldexp_f32 v71, v71, v69
	v_ldexp_f32 v69, v72, v69
	v_add_f32_e32 v72, -1.0, v71
	v_add_f32_e32 v73, 1.0, v72
	v_sub_f32_e32 v73, v71, v73
	v_add_f32_e32 v73, v69, v73
	v_add_f32_e32 v74, v72, v73
	v_sub_f32_e32 v72, v74, v72
	v_sub_f32_e32 v72, v73, v72
	v_add_f32_e32 v73, 1.0, v71
	v_add_f32_e32 v75, -1.0, v73
	v_sub_f32_e32 v71, v71, v75
	v_add_f32_e32 v69, v69, v71
	v_add_f32_e32 v71, v73, v69
	v_sub_f32_e32 v73, v71, v73
	v_sub_f32_e32 v69, v69, v73
	v_rcp_f32_e32 v73, v71
	v_cvt_f32_i32_e32 v68, v68
	v_cmp_neq_f32_e32 vcc, s8, v67
	v_mul_f32_e32 v75, v74, v73
	v_mul_f32_e32 v76, v71, v75
	v_fma_f32 v77, v75, v71, -v76
	v_fmac_f32_e32 v77, v75, v69
	v_add_f32_e32 v78, v76, v77
	v_sub_f32_e32 v79, v74, v78
	v_sub_f32_e32 v74, v74, v79
	v_sub_f32_e32 v76, v78, v76
	v_sub_f32_e32 v74, v74, v78
	v_add_f32_e32 v72, v72, v74
	v_sub_f32_e32 v74, v76, v77
	v_add_f32_e32 v72, v74, v72
	v_add_f32_e32 v74, v79, v72
	v_mul_f32_e32 v76, v73, v74
	v_mul_f32_e32 v77, v71, v76
	v_fma_f32 v71, v76, v71, -v77
	v_fmac_f32_e32 v71, v76, v69
	v_sub_f32_e32 v69, v79, v74
	v_add_f32_e32 v69, v72, v69
	v_add_f32_e32 v72, v77, v71
	v_sub_f32_e32 v78, v74, v72
	v_sub_f32_e32 v74, v74, v78
	v_sub_f32_e32 v77, v72, v77
	v_sub_f32_e32 v72, v74, v72
	v_add_f32_e32 v69, v69, v72
	v_sub_f32_e32 v71, v77, v71
	v_add_f32_e32 v69, v71, v69
	v_add_f32_e32 v71, v75, v76
	v_add_f32_e32 v69, v78, v69
	v_sub_f32_e32 v72, v71, v75
	v_mul_f32_e32 v69, v73, v69
	v_sub_f32_e32 v72, v76, v72
	v_add_f32_e32 v69, v72, v69
	v_mul_f32_e32 v75, 0x3f317218, v68
	v_add_f32_e32 v72, v71, v69
	v_fma_f32 v76, v68, s7, -v75
	v_mul_f32_e32 v73, v72, v72
	v_fmac_f32_e32 v76, 0xb102e308, v68
	v_sub_f32_e32 v68, v72, v71
	v_fmamk_f32 v74, v73, 0x3e9b6dac, v214
	v_sub_f32_e32 v68, v69, v68
	v_add_f32_e32 v69, v75, v76
	v_fmaak_f32 v74, v73, v74, 0x3f2aaada
	v_sub_f32_e32 v71, v69, v75
	v_ldexp_f32 v75, v72, 1
	v_mul_f32_e32 v72, v72, v73
	v_mul_f32_e32 v72, v72, v74
	v_add_f32_e32 v73, v75, v72
	v_sub_f32_e32 v74, v73, v75
	v_ldexp_f32 v68, v68, 1
	v_sub_f32_e32 v72, v72, v74
	v_add_f32_e32 v68, v68, v72
	v_add_f32_e32 v72, v73, v68
	v_sub_f32_e32 v73, v72, v73
	v_sub_f32_e32 v68, v68, v73
	v_add_f32_e32 v73, v69, v72
	v_sub_f32_e32 v74, v73, v69
	v_sub_f32_e32 v75, v73, v74
	v_sub_f32_e32 v71, v76, v71
	v_sub_f32_e32 v69, v69, v75
	v_sub_f32_e32 v72, v72, v74
	v_add_f32_e32 v69, v72, v69
	v_add_f32_e32 v72, v71, v68
	v_sub_f32_e32 v74, v72, v71
;     __device__ __forceinline__ void operator()(const AccT& acc, const pg8::Unit& u, int wr, int wc, int fr, int fq) const {
;     ...
;                     } else if (wc == 1 && fq == 0) {
; #pragma unroll
;                         for (int n = 0; n < 2; ++n)
; #pragma unroll
;                             for (int j = 0; j < 4; ++j) {
;                                 const float x = acc[ai][0][m][n][j] * rs + bfg[4 * n + j];
;                                 lf[(4 * n + j) * MROWS + row] = fminf(x, 0.f) - log1pf(__expf(-fabsf(x)));
	v_sub_f32_e32 v75, v72, v74
	v_sub_f32_e32 v71, v71, v75
	v_sub_f32_e32 v68, v68, v74
	v_add_f32_e32 v69, v72, v69
	v_add_f32_e32 v68, v68, v71
	v_add_f32_e32 v71, v73, v69
	v_sub_f32_e32 v72, v71, v73
	v_sub_f32_e32 v69, v69, v72
	v_add_f32_e32 v68, v68, v69
	v_add_f32_e32 v68, v71, v68
	v_cndmask_b32_e32 v68, v221, v68, vcc
	v_cmp_ngt_f32_e32 vcc, -1.0, v67
	s_nop 1
	v_cndmask_b32_e32 v68, v222, v68, vcc
	v_cmp_neq_f32_e32 vcc, -1.0, v67
	s_nop 1
	v_cndmask_b32_e32 v68, v219, v68, vcc
	v_cmp_lt_f32_e64 vcc, |v67|, s9
	s_nop 1
	v_cndmask_b32_e32 v67, v68, v67, vcc
	v_sub_f32_e32 v70, v70, v67
	global_store_dword v251, v70, s[52:53]
	v_add_f32_e32 v67, v249, v238
	v_min_f32_e32 v70, 0, v67
	v_mul_f32_e64 v67, |v67|, s3
	v_exp_f32_e32 v67, v67
	s_nop 0
	v_add_f32_e32 v71, 1.0, v67
	v_add_f32_e32 v68, -1.0, v71
	v_sub_f32_e32 v69, v68, v71
	v_add_f32_e32 v69, 1.0, v69
	v_sub_f32_e32 v68, v67, v68
	v_add_f32_e32 v72, v68, v69
	v_frexp_mant_f32_e32 v68, v71
	v_cmp_gt_f32_e32 vcc, s6, v68
	v_cvt_f64_f32_e32 v[68:69], v71
	v_frexp_exp_i32_f64_e32 v68, v[68:69]
	v_subbrev_co_u32_e32 v68, vcc, 0, v68, vcc
	v_sub_u32_e32 v69, 0, v68
	v_ldexp_f32 v71, v71, v69
	v_ldexp_f32 v69, v72, v69
	v_add_f32_e32 v72, -1.0, v71
	v_add_f32_e32 v73, 1.0, v72
	v_sub_f32_e32 v73, v71, v73
	v_add_f32_e32 v73, v69, v73
	v_add_f32_e32 v74, v72, v73
	v_sub_f32_e32 v72, v74, v72
	v_sub_f32_e32 v72, v73, v72
	v_add_f32_e32 v73, 1.0, v71
	v_add_f32_e32 v75, -1.0, v73
	v_sub_f32_e32 v71, v71, v75
	v_add_f32_e32 v69, v69, v71
	v_add_f32_e32 v71, v73, v69
	v_sub_f32_e32 v73, v71, v73
	v_sub_f32_e32 v69, v69, v73
	v_rcp_f32_e32 v73, v71
	v_cvt_f32_i32_e32 v68, v68
	v_cmp_neq_f32_e32 vcc, s8, v67
	v_mul_f32_e32 v75, v74, v73
	v_mul_f32_e32 v76, v71, v75
	v_fma_f32 v77, v75, v71, -v76
	v_fmac_f32_e32 v77, v75, v69
	v_add_f32_e32 v78, v76, v77
	v_sub_f32_e32 v79, v74, v78
	v_sub_f32_e32 v74, v74, v79
	v_sub_f32_e32 v76, v78, v76
	v_sub_f32_e32 v74, v74, v78
	v_add_f32_e32 v72, v72, v74
	v_sub_f32_e32 v74, v76, v77
	v_add_f32_e32 v72, v74, v72
	v_add_f32_e32 v74, v79, v72
	v_mul_f32_e32 v76, v73, v74
	v_mul_f32_e32 v77, v71, v76
	v_fma_f32 v71, v76, v71, -v77
	v_fmac_f32_e32 v71, v76, v69
	v_sub_f32_e32 v69, v79, v74
	v_add_f32_e32 v69, v72, v69
	v_add_f32_e32 v72, v77, v71
	v_sub_f32_e32 v78, v74, v72
	v_sub_f32_e32 v74, v74, v78
	v_sub_f32_e32 v77, v72, v77
	v_sub_f32_e32 v72, v74, v72
	v_add_f32_e32 v69, v69, v72
	v_sub_f32_e32 v71, v77, v71
	v_add_f32_e32 v69, v71, v69
	v_add_f32_e32 v71, v75, v76
	v_add_f32_e32 v69, v78, v69
	v_sub_f32_e32 v72, v71, v75
	v_mul_f32_e32 v69, v73, v69
	v_sub_f32_e32 v72, v76, v72
	v_add_f32_e32 v69, v72, v69
	v_mul_f32_e32 v75, 0x3f317218, v68
	v_add_f32_e32 v72, v71, v69
	v_fma_f32 v76, v68, s7, -v75
	v_mul_f32_e32 v73, v72, v72
	v_fmac_f32_e32 v76, 0xb102e308, v68
	v_sub_f32_e32 v68, v72, v71
	v_fmamk_f32 v74, v73, 0x3e9b6dac, v214
	v_sub_f32_e32 v68, v69, v68
	v_add_f32_e32 v69, v75, v76
	v_fmaak_f32 v74, v73, v74, 0x3f2aaada
	v_sub_f32_e32 v71, v69, v75
	v_ldexp_f32 v75, v72, 1
	v_mul_f32_e32 v72, v72, v73
	v_mul_f32_e32 v72, v72, v74
	v_add_f32_e32 v73, v75, v72
	v_sub_f32_e32 v74, v73, v75
	v_ldexp_f32 v68, v68, 1
	v_sub_f32_e32 v72, v72, v74
	v_add_f32_e32 v68, v68, v72
	v_add_f32_e32 v72, v73, v68
	v_sub_f32_e32 v73, v72, v73
	v_sub_f32_e32 v68, v68, v73
	v_add_f32_e32 v73, v69, v72
	v_sub_f32_e32 v74, v73, v69
	v_sub_f32_e32 v75, v73, v74
	v_sub_f32_e32 v71, v76, v71
	v_sub_f32_e32 v69, v69, v75
	v_sub_f32_e32 v72, v72, v74
	v_add_f32_e32 v69, v72, v69
	v_add_f32_e32 v72, v71, v68
	v_sub_f32_e32 v74, v72, v71
	v_sub_f32_e32 v75, v72, v74
	v_sub_f32_e32 v71, v71, v75
	v_sub_f32_e32 v68, v68, v74
	v_add_f32_e32 v69, v72, v69
	v_add_f32_e32 v68, v68, v71
	v_add_f32_e32 v71, v73, v69
	v_sub_f32_e32 v72, v71, v73
	v_sub_f32_e32 v69, v69, v72
	v_add_f32_e32 v68, v68, v69
	v_add_f32_e32 v68, v71, v68
	v_cndmask_b32_e32 v68, v221, v68, vcc
	v_cmp_ngt_f32_e32 vcc, -1.0, v67
	s_nop 1
	v_cndmask_b32_e32 v68, v222, v68, vcc
	v_cmp_neq_f32_e32 vcc, -1.0, v67
	s_nop 1
	v_cndmask_b32_e32 v68, v219, v68, vcc
	v_cmp_lt_f32_e64 vcc, |v67|, s9
	s_nop 1
	v_cndmask_b32_e32 v67, v68, v67, vcc
	v_sub_f32_e32 v70, v70, v67
	global_store_dword v246, v70, s[52:53]

;     __device__ __forceinline__ void operator()(const AccT& acc, const pg8::Unit& u, int wr, int wc, int fr, int fq) const {
;     ...
;         for (int ai = 0; ai < 2; ++ai)
; #pragma unroll
;             for (int m = 0; m < 4; ++m) {
;                 const int row = row0 + ai * 128 + m * 16;
;                 const float rs = 1.0f;
;                 if (u.pn < 20) {
;     ...
;                     } else if (wc == 1 && fq == 0) {
; #pragma unroll
;                         for (int n = 0; n < 2; ++n)
; #pragma unroll
;                             for (int j = 0; j < 4; ++j) {
;                                 const float x = acc[ai][0][m][n][j] * rs + bfg[4 * n + j];
;                                 lf[(4 * n + j) * MROWS + row] = fminf(x, 0.f) - log1pf(__expf(-fabsf(x)));
.LBB0_1011:
	v_add_u32_e32 v50, 0x90, v150
	s_and_b64 vcc, exec, s[44:45]
	s_mov_b64 s[8:9], -1
	s_cbranch_vccnz .LBB0_1019
	s_and_b64 vcc, exec, s[42:43]
	s_cbranch_vccnz .LBB0_1016
	s_mov_b64 s[70:71], exec
	s_and_b64 s[100:101], exec, s[58:59]
	s_cbranch_scc0 .LBB0_1015
	s_mov_b32 s3, 0xbfb8aa3b
	s_mov_b32 s6, 0x3f2aaaab
	s_mov_b32 s7, 0x3f317218
	s_mov_b32 s8, 0x7f800000
	s_mov_b32 s9, 0x33800000
	s_mov_b32 s2, 0x8000
	s_waitcnt lgkmcnt(0)
	ds_bpermute_b32 v46, v250, v46
	ds_bpermute_b32 v47, v250, v47
	ds_bpermute_b32 v48, v250, v48
	ds_bpermute_b32 v49, v250, v49
	ds_bpermute_b32 v42, v250, v42
	ds_bpermute_b32 v43, v250, v43
	ds_bpermute_b32 v44, v250, v44
	ds_bpermute_b32 v45, v250, v45
	s_mov_b32 s100, 0x10800
	v_lshlrev_b32_e32 v251, 2, v50
	s_waitcnt lgkmcnt(0)
	v_mov_b32_e32 v248, v46
	v_mov_b32_e32 v249, v47
	v_cmp_eq_u32_e32 vcc, 1, v239
	s_nop 1
	v_cndmask_b32_e32 v248, v248, v48, vcc
	v_cndmask_b32_e32 v249, v249, v49, vcc
	v_cmp_eq_u32_e32 vcc, 2, v239
	s_nop 1
	v_cndmask_b32_e32 v248, v248, v42, vcc
	v_cndmask_b32_e32 v249, v249, v43, vcc
	v_cmp_eq_u32_e32 vcc, 3, v239
	s_nop 1
	v_cndmask_b32_e32 v248, v248, v44, vcc
	v_cndmask_b32_e32 v249, v249, v45, vcc
	v_mad_u32_u24 v251, v239, s100, v251
	v_add_u32_e32 v246, 0x8400, v251
	v_add_f32_e32 v51, v248, v223
	v_min_f32_e32 v54, 0, v51
	v_mul_f32_e64 v51, |v51|, s3
	v_exp_f32_e32 v51, v51
	s_nop 0
	v_add_f32_e32 v55, 1.0, v51
	v_add_f32_e32 v52, -1.0, v55
	v_sub_f32_e32 v53, v52, v55
	v_add_f32_e32 v53, 1.0, v53
	v_sub_f32_e32 v52, v51, v52
	v_add_f32_e32 v56, v52, v53
	v_frexp_mant_f32_e32 v52, v55
	v_cmp_gt_f32_e32 vcc, s6, v52
	v_cvt_f64_f32_e32 v[52:53], v55
	v_frexp_exp_i32_f64_e32 v52, v[52:53]
	v_subbrev_co_u32_e32 v52, vcc, 0, v52, vcc
	v_sub_u32_e32 v53, 0, v52
	v_ldexp_f32 v55, v55, v53
	v_ldexp_f32 v53, v56, v53
	v_add_f32_e32 v56, -1.0, v55
	v_add_f32_e32 v57, 1.0, v56
	v_sub_f32_e32 v57, v55, v57
	v_add_f32_e32 v57, v53, v57
	v_add_f32_e32 v58, v56, v57
	v_sub_f32_e32 v56, v58, v56
	v_sub_f32_e32 v56, v57, v56
	v_add_f32_e32 v57, 1.0, v55
	v_add_f32_e32 v59, -1.0, v57
	v_sub_f32_e32 v55, v55, v59
	v_add_f32_e32 v53, v53, v55
	v_add_f32_e32 v55, v57, v53
	v_sub_f32_e32 v57, v55, v57
	v_sub_f32_e32 v53, v53, v57
	v_rcp_f32_e32 v57, v55
	v_cvt_f32_i32_e32 v52, v52
	v_cmp_neq_f32_e32 vcc, s8, v51
	v_mul_f32_e32 v59, v58, v57
	v_mul_f32_e32 v60, v55, v59
	v_fma_f32 v61, v59, v55, -v60
	v_fmac_f32_e32 v61, v59, v53
	v_add_f32_e32 v62, v60, v61
	v_sub_f32_e32 v63, v58, v62
	v_sub_f32_e32 v58, v58, v63
	v_sub_f32_e32 v60, v62, v60
	v_sub_f32_e32 v58, v58, v62
	v_add_f32_e32 v56, v56, v58
	v_sub_f32_e32 v58, v60, v61
	v_add_f32_e32 v56, v58, v56
	v_add_f32_e32 v58, v63, v56
	v_mul_f32_e32 v60, v57, v58
	v_mul_f32_e32 v61, v55, v60
	v_fma_f32 v55, v60, v55, -v61
	v_fmac_f32_e32 v55, v60, v53
	v_sub_f32_e32 v53, v63, v58
	v_add_f32_e32 v53, v56, v53
	v_add_f32_e32 v56, v61, v55
	v_sub_f32_e32 v62, v58, v56
	v_sub_f32_e32 v58, v58, v62
	v_sub_f32_e32 v61, v56, v61
	v_sub_f32_e32 v56, v58, v56
	v_add_f32_e32 v53, v53, v56
	v_sub_f32_e32 v55, v61, v55
	v_add_f32_e32 v53, v55, v53
	v_add_f32_e32 v55, v59, v60
	v_add_f32_e32 v53, v62, v53
	v_sub_f32_e32 v56, v55, v59
	v_mul_f32_e32 v53, v57, v53
	v_sub_f32_e32 v56, v60, v56
	v_add_f32_e32 v53, v56, v53
	v_mul_f32_e32 v59, 0x3f317218, v52
	v_add_f32_e32 v56, v55, v53
	v_fma_f32 v60, v52, s7, -v59
	v_mul_f32_e32 v57, v56, v56
	v_fmac_f32_e32 v60, 0xb102e308, v52
	v_sub_f32_e32 v52, v56, v55
	v_fmamk_f32 v58, v57, 0x3e9b6dac, v214
	v_sub_f32_e32 v52, v53, v52
	v_add_f32_e32 v53, v59, v60
	v_fmaak_f32 v58, v57, v58, 0x3f2aaada
	v_sub_f32_e32 v55, v53, v59
	v_ldexp_f32 v59, v56, 1
	v_mul_f32_e32 v56, v56, v57
	v_mul_f32_e32 v56, v56, v58
	v_add_f32_e32 v57, v59, v56
	v_sub_f32_e32 v58, v57, v59
	v_ldexp_f32 v52, v52, 1
	v_sub_f32_e32 v56, v56, v58
	v_add_f32_e32 v52, v52, v56
	v_add_f32_e32 v56, v57, v52
	v_sub_f32_e32 v57, v56, v57
	v_sub_f32_e32 v52, v52, v57
	v_add_f32_e32 v57, v53, v56
	v_sub_f32_e32 v58, v57, v53
	v_sub_f32_e32 v59, v57, v58
	v_sub_f32_e32 v55, v60, v55
	v_sub_f32_e32 v53, v53, v59
	v_sub_f32_e32 v56, v56, v58
	v_add_f32_e32 v53, v56, v53
	v_add_f32_e32 v56, v55, v52
	v_sub_f32_e32 v58, v56, v55
;     __device__ __forceinline__ void operator()(const AccT& acc, const pg8::Unit& u, int wr, int wc, int fr, int fq) const {
;     ...
;                     } else if (wc == 1 && fq == 0) {
; #pragma unroll
;                         for (int n = 0; n < 2; ++n)
; #pragma unroll
;                             for (int j = 0; j < 4; ++j) {
;                                 const float x = acc[ai][0][m][n][j] * rs + bfg[4 * n + j];
;                                 lf[(4 * n + j) * MROWS + row] = fminf(x, 0.f) - log1pf(__expf(-fabsf(x)));
	v_sub_f32_e32 v59, v56, v58
	v_sub_f32_e32 v55, v55, v59
	v_sub_f32_e32 v52, v52, v58
	v_add_f32_e32 v53, v56, v53
	v_add_f32_e32 v52, v52, v55
	v_add_f32_e32 v55, v57, v53
	v_sub_f32_e32 v56, v55, v57
	v_sub_f32_e32 v53, v53, v56
	v_add_f32_e32 v52, v52, v53
	v_add_f32_e32 v52, v55, v52
	v_cndmask_b32_e32 v52, v221, v52, vcc
	v_cmp_ngt_f32_e32 vcc, -1.0, v51
	s_nop 1
	v_cndmask_b32_e32 v52, v222, v52, vcc
	v_cmp_neq_f32_e32 vcc, -1.0, v51
	s_nop 1
	v_cndmask_b32_e32 v52, v219, v52, vcc
	v_cmp_lt_f32_e64 vcc, |v51|, s9
	s_nop 1
	v_cndmask_b32_e32 v51, v52, v51, vcc
	v_sub_f32_e32 v54, v54, v51
	global_store_dword v251, v54, s[52:53]
	v_add_f32_e32 v51, v249, v238
	v_min_f32_e32 v54, 0, v51
	v_mul_f32_e64 v51, |v51|, s3
	v_exp_f32_e32 v51, v51
	s_nop 0
	v_add_f32_e32 v55, 1.0, v51
	v_add_f32_e32 v52, -1.0, v55
	v_sub_f32_e32 v53, v52, v55
	v_add_f32_e32 v53, 1.0, v53
	v_sub_f32_e32 v52, v51, v52
	v_add_f32_e32 v56, v52, v53
	v_frexp_mant_f32_e32 v52, v55
	v_cmp_gt_f32_e32 vcc, s6, v52
	v_cvt_f64_f32_e32 v[52:53], v55
	v_frexp_exp_i32_f64_e32 v52, v[52:53]
	v_subbrev_co_u32_e32 v52, vcc, 0, v52, vcc
	v_sub_u32_e32 v53, 0, v52
	v_ldexp_f32 v55, v55, v53
	v_ldexp_f32 v53, v56, v53
	v_add_f32_e32 v56, -1.0, v55
	v_add_f32_e32 v57, 1.0, v56
	v_sub_f32_e32 v57, v55, v57
	v_add_f32_e32 v57, v53, v57
	v_add_f32_e32 v58, v56, v57
	v_sub_f32_e32 v56, v58, v56
	v_sub_f32_e32 v56, v57, v56
	v_add_f32_e32 v57, 1.0, v55
	v_add_f32_e32 v59, -1.0, v57
	v_sub_f32_e32 v55, v55, v59
	v_add_f32_e32 v53, v53, v55
	v_add_f32_e32 v55, v57, v53
	v_sub_f32_e32 v57, v55, v57
	v_sub_f32_e32 v53, v53, v57
	v_rcp_f32_e32 v57, v55
	v_cvt_f32_i32_e32 v52, v52
	v_cmp_neq_f32_e32 vcc, s8, v51
	v_mul_f32_e32 v59, v58, v57
	v_mul_f32_e32 v60, v55, v59
	v_fma_f32 v61, v59, v55, -v60
	v_fmac_f32_e32 v61, v59, v53
	v_add_f32_e32 v62, v60, v61
	v_sub_f32_e32 v63, v58, v62
	v_sub_f32_e32 v58, v58, v63
	v_sub_f32_e32 v60, v62, v60
	v_sub_f32_e32 v58, v58, v62
	v_add_f32_e32 v56, v56, v58
	v_sub_f32_e32 v58, v60, v61
	v_add_f32_e32 v56, v58, v56
	v_add_f32_e32 v58, v63, v56
	v_mul_f32_e32 v60, v57, v58
	v_mul_f32_e32 v61, v55, v60
	v_fma_f32 v55, v60, v55, -v61
	v_fmac_f32_e32 v55, v60, v53
	v_sub_f32_e32 v53, v63, v58
	v_add_f32_e32 v53, v56, v53
	v_add_f32_e32 v56, v61, v55
	v_sub_f32_e32 v62, v58, v56
	v_sub_f32_e32 v58, v58, v62
	v_sub_f32_e32 v61, v56, v61
	v_sub_f32_e32 v56, v58, v56
	v_add_f32_e32 v53, v53, v56
	v_sub_f32_e32 v55, v61, v55
	v_add_f32_e32 v53, v55, v53
	v_add_f32_e32 v55, v59, v60
	v_add_f32_e32 v53, v62, v53
	v_sub_f32_e32 v56, v55, v59
	v_mul_f32_e32 v53, v57, v53
	v_sub_f32_e32 v56, v60, v56
	v_add_f32_e32 v53, v56, v53
	v_mul_f32_e32 v59, 0x3f317218, v52
	v_add_f32_e32 v56, v55, v53
	v_fma_f32 v60, v52, s7, -v59
	v_mul_f32_e32 v57, v56, v56
	v_fmac_f32_e32 v60, 0xb102e308, v52
	v_sub_f32_e32 v52, v56, v55
	v_fmamk_f32 v58, v57, 0x3e9b6dac, v214
	v_sub_f32_e32 v52, v53, v52
	v_add_f32_e32 v53, v59, v60
	v_fmaak_f32 v58, v57, v58, 0x3f2aaada
	v_sub_f32_e32 v55, v53, v59
	v_ldexp_f32 v59, v56, 1
	v_mul_f32_e32 v56, v56, v57
	v_mul_f32_e32 v56, v56, v58
	v_add_f32_e32 v57, v59, v56
	v_sub_f32_e32 v58, v57, v59
	v_ldexp_f32 v52, v52, 1
	v_sub_f32_e32 v56, v56, v58
	v_add_f32_e32 v52, v52, v56
	v_add_f32_e32 v56, v57, v52
	v_sub_f32_e32 v57, v56, v57
	v_sub_f32_e32 v52, v52, v57
	v_add_f32_e32 v57, v53, v56
	v_sub_f32_e32 v58, v57, v53
	v_sub_f32_e32 v59, v57, v58
	v_sub_f32_e32 v55, v60, v55
	v_sub_f32_e32 v53, v53, v59
	v_sub_f32_e32 v56, v56, v58
	v_add_f32_e32 v53, v56, v53
	v_add_f32_e32 v56, v55, v52
	v_sub_f32_e32 v58, v56, v55
	v_sub_f32_e32 v59, v56, v58
	v_sub_f32_e32 v55, v55, v59
	v_sub_f32_e32 v52, v52, v58
	v_add_f32_e32 v53, v56, v53
	v_add_f32_e32 v52, v52, v55
	v_add_f32_e32 v55, v57, v53
	v_sub_f32_e32 v56, v55, v57
	v_sub_f32_e32 v53, v53, v56
	v_add_f32_e32 v52, v52, v53
	v_add_f32_e32 v52, v55, v52
	v_cndmask_b32_e32 v52, v221, v52, vcc
	v_cmp_ngt_f32_e32 vcc, -1.0, v51
	s_nop 1
	v_cndmask_b32_e32 v52, v222, v52, vcc
	v_cmp_neq_f32_e32 vcc, -1.0, v51
	s_nop 1
	v_cndmask_b32_e32 v52, v219, v52, vcc
	v_cmp_lt_f32_e64 vcc, |v51|, s9
	s_nop 1
	v_cndmask_b32_e32 v51, v52, v51, vcc
	v_sub_f32_e32 v54, v54, v51
	global_store_dword v246, v54, s[52:53]

;     __device__ __forceinline__ void operator()(const AccT& acc, const pg8::Unit& u, int wr, int wc, int fr, int fq) const {
;     ...
;         for (int ai = 0; ai < 2; ++ai)
; #pragma unroll
;             for (int m = 0; m < 4; ++m) {
;                 const int row = row0 + ai * 128 + m * 16;
;                 const float rs = 1.0f;
;                 if (u.pn < 20) {
;     ...
;                     } else if (wc == 1 && fq == 0) {
; #pragma unroll
;                         for (int n = 0; n < 2; ++n)
; #pragma unroll
;                             for (int j = 0; j < 4; ++j) {
;                                 const float x = acc[ai][0][m][n][j] * rs + bfg[4 * n + j];
;                                 lf[(4 * n + j) * MROWS + row] = fminf(x, 0.f) - log1pf(__expf(-fabsf(x)));
.LBB0_1024:
	v_add_u32_e32 v34, 0xa0, v150
	s_and_b64 vcc, exec, s[44:45]
	s_mov_b64 s[8:9], -1
	s_cbranch_vccnz .LBB0_1032
	s_and_b64 vcc, exec, s[42:43]
	s_cbranch_vccnz .LBB0_1029
	s_mov_b64 s[70:71], exec
	s_and_b64 s[100:101], exec, s[58:59]
	s_cbranch_scc0 .LBB0_1028
	s_mov_b32 s3, 0xbfb8aa3b
	s_mov_b32 s6, 0x3f2aaaab
	s_mov_b32 s7, 0x3f317218
	s_mov_b32 s8, 0x7f800000
	s_mov_b32 s9, 0x33800000
	s_mov_b32 s2, 0x8000
	s_waitcnt lgkmcnt(0)
	ds_bpermute_b32 v30, v250, v30
	ds_bpermute_b32 v31, v250, v31
	ds_bpermute_b32 v32, v250, v32
	ds_bpermute_b32 v33, v250, v33
	ds_bpermute_b32 v26, v250, v26
	ds_bpermute_b32 v27, v250, v27
	ds_bpermute_b32 v28, v250, v28
	ds_bpermute_b32 v29, v250, v29
	s_mov_b32 s100, 0x10800
	v_lshlrev_b32_e32 v251, 2, v34
	s_waitcnt lgkmcnt(0)
	v_mov_b32_e32 v248, v30
	v_mov_b32_e32 v249, v31
	v_cmp_eq_u32_e32 vcc, 1, v239
	s_nop 1
	v_cndmask_b32_e32 v248, v248, v32, vcc
	v_cndmask_b32_e32 v249, v249, v33, vcc
	v_cmp_eq_u32_e32 vcc, 2, v239
	s_nop 1
	v_cndmask_b32_e32 v248, v248, v26, vcc
	v_cndmask_b32_e32 v249, v249, v27, vcc
	v_cmp_eq_u32_e32 vcc, 3, v239
	s_nop 1
	v_cndmask_b32_e32 v248, v248, v28, vcc
	v_cndmask_b32_e32 v249, v249, v29, vcc
	v_mad_u32_u24 v251, v239, s100, v251
	v_add_u32_e32 v246, 0x8400, v251
	v_add_f32_e32 v35, v248, v223
	v_min_f32_e32 v38, 0, v35
	v_mul_f32_e64 v35, |v35|, s3
	v_exp_f32_e32 v35, v35
	s_nop 0
	v_add_f32_e32 v39, 1.0, v35
	v_add_f32_e32 v36, -1.0, v39
	v_sub_f32_e32 v37, v36, v39
	v_add_f32_e32 v37, 1.0, v37
	v_sub_f32_e32 v36, v35, v36
	v_add_f32_e32 v40, v36, v37
	v_frexp_mant_f32_e32 v36, v39
	v_cmp_gt_f32_e32 vcc, s6, v36
	v_cvt_f64_f32_e32 v[36:37], v39
	v_frexp_exp_i32_f64_e32 v36, v[36:37]
	v_subbrev_co_u32_e32 v36, vcc, 0, v36, vcc
	v_sub_u32_e32 v37, 0, v36
	v_ldexp_f32 v39, v39, v37
	v_ldexp_f32 v37, v40, v37
	v_add_f32_e32 v40, -1.0, v39
	v_add_f32_e32 v41, 1.0, v40
	v_sub_f32_e32 v41, v39, v41
	v_add_f32_e32 v41, v37, v41
	v_add_f32_e32 v42, v40, v41
	v_sub_f32_e32 v40, v42, v40
	v_sub_f32_e32 v40, v41, v40
	v_add_f32_e32 v41, 1.0, v39
	v_add_f32_e32 v43, -1.0, v41
	v_sub_f32_e32 v39, v39, v43
	v_add_f32_e32 v37, v37, v39
	v_add_f32_e32 v39, v41, v37
	v_sub_f32_e32 v41, v39, v41
	v_sub_f32_e32 v37, v37, v41
	v_rcp_f32_e32 v41, v39
	v_cvt_f32_i32_e32 v36, v36
	v_cmp_neq_f32_e32 vcc, s8, v35
	v_mul_f32_e32 v43, v42, v41
	v_mul_f32_e32 v44, v39, v43
	v_fma_f32 v45, v43, v39, -v44
	v_fmac_f32_e32 v45, v43, v37
	v_add_f32_e32 v46, v44, v45
	v_sub_f32_e32 v47, v42, v46
	v_sub_f32_e32 v42, v42, v47
	v_sub_f32_e32 v44, v46, v44
	v_sub_f32_e32 v42, v42, v46
	v_add_f32_e32 v40, v40, v42
	v_sub_f32_e32 v42, v44, v45
	v_add_f32_e32 v40, v42, v40
	v_add_f32_e32 v42, v47, v40
	v_mul_f32_e32 v44, v41, v42
	v_mul_f32_e32 v45, v39, v44
	v_fma_f32 v39, v44, v39, -v45
	v_fmac_f32_e32 v39, v44, v37
	v_sub_f32_e32 v37, v47, v42
	v_add_f32_e32 v37, v40, v37
	v_add_f32_e32 v40, v45, v39
	v_sub_f32_e32 v46, v42, v40
	v_sub_f32_e32 v42, v42, v46
	v_sub_f32_e32 v45, v40, v45
	v_sub_f32_e32 v40, v42, v40
	v_add_f32_e32 v37, v37, v40
	v_sub_f32_e32 v39, v45, v39
	v_add_f32_e32 v37, v39, v37
	v_add_f32_e32 v39, v43, v44
	v_add_f32_e32 v37, v46, v37
	v_sub_f32_e32 v40, v39, v43
	v_mul_f32_e32 v37, v41, v37
	v_sub_f32_e32 v40, v44, v40
	v_add_f32_e32 v37, v40, v37
	v_mul_f32_e32 v43, 0x3f317218, v36
	v_add_f32_e32 v40, v39, v37
	v_fma_f32 v44, v36, s7, -v43
	v_mul_f32_e32 v41, v40, v40
	v_fmac_f32_e32 v44, 0xb102e308, v36
	v_sub_f32_e32 v36, v40, v39
	v_fmamk_f32 v42, v41, 0x3e9b6dac, v214
	v_sub_f32_e32 v36, v37, v36
	v_add_f32_e32 v37, v43, v44
	v_fmaak_f32 v42, v41, v42, 0x3f2aaada
	v_sub_f32_e32 v39, v37, v43
	v_ldexp_f32 v43, v40, 1
	v_mul_f32_e32 v40, v40, v41
	v_mul_f32_e32 v40, v40, v42
	v_add_f32_e32 v41, v43, v40
	v_sub_f32_e32 v42, v41, v43
	v_ldexp_f32 v36, v36, 1
	v_sub_f32_e32 v40, v40, v42
	v_add_f32_e32 v36, v36, v40
	v_add_f32_e32 v40, v41, v36
	v_sub_f32_e32 v41, v40, v41
	v_sub_f32_e32 v36, v36, v41
	v_add_f32_e32 v41, v37, v40
	v_sub_f32_e32 v42, v41, v37
	v_sub_f32_e32 v43, v41, v42
	v_sub_f32_e32 v39, v44, v39
	v_sub_f32_e32 v37, v37, v43
	v_sub_f32_e32 v40, v40, v42
	v_add_f32_e32 v37, v40, v37
	v_add_f32_e32 v40, v39, v36
	v_sub_f32_e32 v42, v40, v39
;     __device__ __forceinline__ void operator()(const AccT& acc, const pg8::Unit& u, int wr, int wc, int fr, int fq) const {
;     ...
;                     } else if (wc == 1 && fq == 0) {
; #pragma unroll
;                         for (int n = 0; n < 2; ++n)
; #pragma unroll
;                             for (int j = 0; j < 4; ++j) {
;                                 const float x = acc[ai][0][m][n][j] * rs + bfg[4 * n + j];
;                                 lf[(4 * n + j) * MROWS + row] = fminf(x, 0.f) - log1pf(__expf(-fabsf(x)));
	v_sub_f32_e32 v43, v40, v42
	v_sub_f32_e32 v39, v39, v43
	v_sub_f32_e32 v36, v36, v42
	v_add_f32_e32 v37, v40, v37
	v_add_f32_e32 v36, v36, v39
	v_add_f32_e32 v39, v41, v37
	v_sub_f32_e32 v40, v39, v41
	v_sub_f32_e32 v37, v37, v40
	v_add_f32_e32 v36, v36, v37
	v_add_f32_e32 v36, v39, v36
	v_cndmask_b32_e32 v36, v221, v36, vcc
	v_cmp_ngt_f32_e32 vcc, -1.0, v35
	s_nop 1
	v_cndmask_b32_e32 v36, v222, v36, vcc
	v_cmp_neq_f32_e32 vcc, -1.0, v35
	s_nop 1
	v_cndmask_b32_e32 v36, v219, v36, vcc
	v_cmp_lt_f32_e64 vcc, |v35|, s9
	s_nop 1
	v_cndmask_b32_e32 v35, v36, v35, vcc
	v_sub_f32_e32 v38, v38, v35
	global_store_dword v251, v38, s[52:53]
	v_add_f32_e32 v35, v249, v238
	v_min_f32_e32 v38, 0, v35
	v_mul_f32_e64 v35, |v35|, s3
	v_exp_f32_e32 v35, v35
	s_nop 0
	v_add_f32_e32 v39, 1.0, v35
	v_add_f32_e32 v36, -1.0, v39
	v_sub_f32_e32 v37, v36, v39
	v_add_f32_e32 v37, 1.0, v37
	v_sub_f32_e32 v36, v35, v36
	v_add_f32_e32 v40, v36, v37
	v_frexp_mant_f32_e32 v36, v39
	v_cmp_gt_f32_e32 vcc, s6, v36
	v_cvt_f64_f32_e32 v[36:37], v39
	v_frexp_exp_i32_f64_e32 v36, v[36:37]
	v_subbrev_co_u32_e32 v36, vcc, 0, v36, vcc
	v_sub_u32_e32 v37, 0, v36
	v_ldexp_f32 v39, v39, v37
	v_ldexp_f32 v37, v40, v37
	v_add_f32_e32 v40, -1.0, v39
	v_add_f32_e32 v41, 1.0, v40
	v_sub_f32_e32 v41, v39, v41
	v_add_f32_e32 v41, v37, v41
	v_add_f32_e32 v42, v40, v41
	v_sub_f32_e32 v40, v42, v40
	v_sub_f32_e32 v40, v41, v40
	v_add_f32_e32 v41, 1.0, v39
	v_add_f32_e32 v43, -1.0, v41
	v_sub_f32_e32 v39, v39, v43
	v_add_f32_e32 v37, v37, v39
	v_add_f32_e32 v39, v41, v37
	v_sub_f32_e32 v41, v39, v41
	v_sub_f32_e32 v37, v37, v41
	v_rcp_f32_e32 v41, v39
	v_cvt_f32_i32_e32 v36, v36
	v_cmp_neq_f32_e32 vcc, s8, v35
	v_mul_f32_e32 v43, v42, v41
	v_mul_f32_e32 v44, v39, v43
	v_fma_f32 v45, v43, v39, -v44
	v_fmac_f32_e32 v45, v43, v37
	v_add_f32_e32 v46, v44, v45
	v_sub_f32_e32 v47, v42, v46
	v_sub_f32_e32 v42, v42, v47
	v_sub_f32_e32 v44, v46, v44
	v_sub_f32_e32 v42, v42, v46
	v_add_f32_e32 v40, v40, v42
	v_sub_f32_e32 v42, v44, v45
	v_add_f32_e32 v40, v42, v40
	v_add_f32_e32 v42, v47, v40
	v_mul_f32_e32 v44, v41, v42
	v_mul_f32_e32 v45, v39, v44
	v_fma_f32 v39, v44, v39, -v45
	v_fmac_f32_e32 v39, v44, v37
	v_sub_f32_e32 v37, v47, v42
	v_add_f32_e32 v37, v40, v37
	v_add_f32_e32 v40, v45, v39
	v_sub_f32_e32 v46, v42, v40
	v_sub_f32_e32 v42, v42, v46
	v_sub_f32_e32 v45, v40, v45
	v_sub_f32_e32 v40, v42, v40
	v_add_f32_e32 v37, v37, v40
	v_sub_f32_e32 v39, v45, v39
	v_add_f32_e32 v37, v39, v37
	v_add_f32_e32 v39, v43, v44
	v_add_f32_e32 v37, v46, v37
	v_sub_f32_e32 v40, v39, v43
	v_mul_f32_e32 v37, v41, v37
	v_sub_f32_e32 v40, v44, v40
	v_add_f32_e32 v37, v40, v37
	v_mul_f32_e32 v43, 0x3f317218, v36
	v_add_f32_e32 v40, v39, v37
	v_fma_f32 v44, v36, s7, -v43
	v_mul_f32_e32 v41, v40, v40
	v_fmac_f32_e32 v44, 0xb102e308, v36
	v_sub_f32_e32 v36, v40, v39
	v_fmamk_f32 v42, v41, 0x3e9b6dac, v214
	v_sub_f32_e32 v36, v37, v36
	v_add_f32_e32 v37, v43, v44
	v_fmaak_f32 v42, v41, v42, 0x3f2aaada
	v_sub_f32_e32 v39, v37, v43
	v_ldexp_f32 v43, v40, 1
	v_mul_f32_e32 v40, v40, v41
	v_mul_f32_e32 v40, v40, v42
	v_add_f32_e32 v41, v43, v40
	v_sub_f32_e32 v42, v41, v43
	v_ldexp_f32 v36, v36, 1
	v_sub_f32_e32 v40, v40, v42
	v_add_f32_e32 v36, v36, v40
	v_add_f32_e32 v40, v41, v36
	v_sub_f32_e32 v41, v40, v41
	v_sub_f32_e32 v36, v36, v41
	v_add_f32_e32 v41, v37, v40
	v_sub_f32_e32 v42, v41, v37
	v_sub_f32_e32 v43, v41, v42
	v_sub_f32_e32 v39, v44, v39
	v_sub_f32_e32 v37, v37, v43
	v_sub_f32_e32 v40, v40, v42
	v_add_f32_e32 v37, v40, v37
	v_add_f32_e32 v40, v39, v36
	v_sub_f32_e32 v42, v40, v39
	v_sub_f32_e32 v43, v40, v42
	v_sub_f32_e32 v39, v39, v43
	v_sub_f32_e32 v36, v36, v42
	v_add_f32_e32 v37, v40, v37
	v_add_f32_e32 v36, v36, v39
	v_add_f32_e32 v39, v41, v37
	v_sub_f32_e32 v40, v39, v41
	v_sub_f32_e32 v37, v37, v40
	v_add_f32_e32 v36, v36, v37
	v_add_f32_e32 v36, v39, v36
	v_cndmask_b32_e32 v36, v221, v36, vcc
	v_cmp_ngt_f32_e32 vcc, -1.0, v35
	s_nop 1
	v_cndmask_b32_e32 v36, v222, v36, vcc
	v_cmp_neq_f32_e32 vcc, -1.0, v35
	s_nop 1
	v_cndmask_b32_e32 v36, v219, v36, vcc
	v_cmp_lt_f32_e64 vcc, |v35|, s9
	s_nop 1
	v_cndmask_b32_e32 v35, v36, v35, vcc
	v_sub_f32_e32 v38, v38, v35
	global_store_dword v246, v38, s[52:53]

;     __device__ __forceinline__ void operator()(const AccT& acc, const pg8::Unit& u, int wr, int wc, int fr, int fq) const {
;     ...
;         for (int ai = 0; ai < 2; ++ai)
; #pragma unroll
;             for (int m = 0; m < 4; ++m) {
;                 const int row = row0 + ai * 128 + m * 16;
;                 const float rs = 1.0f;
;                 if (u.pn < 20) {
;     ...
;                     } else if (wc == 1 && fq == 0) {
; #pragma unroll
;                         for (int n = 0; n < 2; ++n)
; #pragma unroll
;                             for (int j = 0; j < 4; ++j) {
;                                 const float x = acc[ai][0][m][n][j] * rs + bfg[4 * n + j];
;                                 lf[(4 * n + j) * MROWS + row] = fminf(x, 0.f) - log1pf(__expf(-fabsf(x)));
.LBB0_1037:
	v_add_u32_e32 v18, 0xb0, v150
	s_and_b64 vcc, exec, s[44:45]
	s_mov_b64 s[8:9], -1
	s_cbranch_vccnz .LBB0_1045
	s_and_b64 vcc, exec, s[42:43]
	s_cbranch_vccnz .LBB0_1042
	s_mov_b64 s[42:43], exec
	s_and_b64 s[100:101], exec, s[58:59]
	s_cbranch_scc0 .LBB0_1041
	s_mov_b32 s3, 0xbfb8aa3b
	s_mov_b32 s6, 0x3f2aaaab
	s_mov_b32 s7, 0x3f317218
	s_mov_b32 s8, 0x7f800000
	s_mov_b32 s9, 0x33800000
	s_mov_b32 s2, 0x8000
	s_waitcnt lgkmcnt(0)
	ds_bpermute_b32 v14, v250, v14
	ds_bpermute_b32 v15, v250, v15
	ds_bpermute_b32 v16, v250, v16
	ds_bpermute_b32 v17, v250, v17
	ds_bpermute_b32 v10, v250, v10
	ds_bpermute_b32 v11, v250, v11
	ds_bpermute_b32 v12, v250, v12
	ds_bpermute_b32 v13, v250, v13
	s_mov_b32 s100, 0x10800
	v_lshlrev_b32_e32 v251, 2, v18
	s_waitcnt lgkmcnt(0)
	v_mov_b32_e32 v248, v14
	v_mov_b32_e32 v249, v15
	v_cmp_eq_u32_e32 vcc, 1, v239
	s_nop 1
	v_cndmask_b32_e32 v248, v248, v16, vcc
	v_cndmask_b32_e32 v249, v249, v17, vcc
	v_cmp_eq_u32_e32 vcc, 2, v239
	s_nop 1
	v_cndmask_b32_e32 v248, v248, v10, vcc
	v_cndmask_b32_e32 v249, v249, v11, vcc
	v_cmp_eq_u32_e32 vcc, 3, v239
	s_nop 1
	v_cndmask_b32_e32 v248, v248, v12, vcc
	v_cndmask_b32_e32 v249, v249, v13, vcc
	v_mad_u32_u24 v251, v239, s100, v251
	v_add_u32_e32 v246, 0x8400, v251
	v_add_f32_e32 v19, v248, v223
	v_min_f32_e32 v22, 0, v19
	v_mul_f32_e64 v19, |v19|, s3
	v_exp_f32_e32 v19, v19
	s_nop 0
	v_add_f32_e32 v23, 1.0, v19
	v_add_f32_e32 v20, -1.0, v23
	v_sub_f32_e32 v21, v20, v23
	v_add_f32_e32 v21, 1.0, v21
	v_sub_f32_e32 v20, v19, v20
	v_add_f32_e32 v24, v20, v21
	v_frexp_mant_f32_e32 v20, v23
	v_cmp_gt_f32_e32 vcc, s6, v20
	v_cvt_f64_f32_e32 v[20:21], v23
	v_frexp_exp_i32_f64_e32 v20, v[20:21]
	v_subbrev_co_u32_e32 v20, vcc, 0, v20, vcc
	v_sub_u32_e32 v21, 0, v20
	v_ldexp_f32 v23, v23, v21
	v_ldexp_f32 v21, v24, v21
	v_add_f32_e32 v24, -1.0, v23
	v_add_f32_e32 v25, 1.0, v24
	v_sub_f32_e32 v25, v23, v25
	v_add_f32_e32 v25, v21, v25
	v_add_f32_e32 v26, v24, v25
	v_sub_f32_e32 v24, v26, v24
	v_sub_f32_e32 v24, v25, v24
	v_add_f32_e32 v25, 1.0, v23
	v_add_f32_e32 v27, -1.0, v25
	v_sub_f32_e32 v23, v23, v27
	v_add_f32_e32 v21, v21, v23
	v_add_f32_e32 v23, v25, v21
	v_sub_f32_e32 v25, v23, v25
	v_sub_f32_e32 v21, v21, v25
	v_rcp_f32_e32 v25, v23
	v_cvt_f32_i32_e32 v20, v20
	v_cmp_neq_f32_e32 vcc, s8, v19
	v_mul_f32_e32 v27, v26, v25
	v_mul_f32_e32 v28, v23, v27
	v_fma_f32 v29, v27, v23, -v28
	v_fmac_f32_e32 v29, v27, v21
	v_add_f32_e32 v30, v28, v29
	v_sub_f32_e32 v31, v26, v30
	v_sub_f32_e32 v26, v26, v31
	v_sub_f32_e32 v28, v30, v28
	v_sub_f32_e32 v26, v26, v30
	v_add_f32_e32 v24, v24, v26
	v_sub_f32_e32 v26, v28, v29
	v_add_f32_e32 v24, v26, v24
	v_add_f32_e32 v26, v31, v24
	v_mul_f32_e32 v28, v25, v26
	v_mul_f32_e32 v29, v23, v28
	v_fma_f32 v23, v28, v23, -v29
	v_fmac_f32_e32 v23, v28, v21
	v_sub_f32_e32 v21, v31, v26
	v_add_f32_e32 v21, v24, v21
	v_add_f32_e32 v24, v29, v23
	v_sub_f32_e32 v30, v26, v24
	v_sub_f32_e32 v26, v26, v30
	v_sub_f32_e32 v29, v24, v29
	v_sub_f32_e32 v24, v26, v24
	v_add_f32_e32 v21, v21, v24
	v_sub_f32_e32 v23, v29, v23
	v_add_f32_e32 v21, v23, v21
	v_add_f32_e32 v23, v27, v28
	v_add_f32_e32 v21, v30, v21
	v_sub_f32_e32 v24, v23, v27
	v_mul_f32_e32 v21, v25, v21
	v_sub_f32_e32 v24, v28, v24
	v_add_f32_e32 v21, v24, v21
	v_mul_f32_e32 v27, 0x3f317218, v20
	v_add_f32_e32 v24, v23, v21
	v_fma_f32 v28, v20, s7, -v27
	v_mul_f32_e32 v25, v24, v24
	v_fmac_f32_e32 v28, 0xb102e308, v20
	v_sub_f32_e32 v20, v24, v23
	v_fmamk_f32 v26, v25, 0x3e9b6dac, v214
	v_sub_f32_e32 v20, v21, v20
	v_add_f32_e32 v21, v27, v28
	v_fmaak_f32 v26, v25, v26, 0x3f2aaada
	v_sub_f32_e32 v23, v21, v27
	v_ldexp_f32 v27, v24, 1
	v_mul_f32_e32 v24, v24, v25
	v_mul_f32_e32 v24, v24, v26
	v_add_f32_e32 v25, v27, v24
	v_sub_f32_e32 v26, v25, v27
	v_ldexp_f32 v20, v20, 1
	v_sub_f32_e32 v24, v24, v26
	v_add_f32_e32 v20, v20, v24
	v_add_f32_e32 v24, v25, v20
	v_sub_f32_e32 v25, v24, v25
	v_sub_f32_e32 v20, v20, v25
	v_add_f32_e32 v25, v21, v24
	v_sub_f32_e32 v26, v25, v21
	v_sub_f32_e32 v27, v25, v26
	v_sub_f32_e32 v23, v28, v23
	v_sub_f32_e32 v21, v21, v27
	v_sub_f32_e32 v24, v24, v26
	v_add_f32_e32 v21, v24, v21
	v_add_f32_e32 v24, v23, v20
	v_sub_f32_e32 v26, v24, v23
;     __device__ __forceinline__ void operator()(const AccT& acc, const pg8::Unit& u, int wr, int wc, int fr, int fq) const {
;     ...
;                     } else if (wc == 1 && fq == 0) {
; #pragma unroll
;                         for (int n = 0; n < 2; ++n)
; #pragma unroll
;                             for (int j = 0; j < 4; ++j) {
;                                 const float x = acc[ai][0][m][n][j] * rs + bfg[4 * n + j];
;                                 lf[(4 * n + j) * MROWS + row] = fminf(x, 0.f) - log1pf(__expf(-fabsf(x)));
	v_sub_f32_e32 v27, v24, v26
	v_sub_f32_e32 v23, v23, v27
	v_sub_f32_e32 v20, v20, v26
	v_add_f32_e32 v21, v24, v21
	v_add_f32_e32 v20, v20, v23
	v_add_f32_e32 v23, v25, v21
	v_sub_f32_e32 v24, v23, v25
	v_sub_f32_e32 v21, v21, v24
	v_add_f32_e32 v20, v20, v21
	v_add_f32_e32 v20, v23, v20
	v_cndmask_b32_e32 v20, v221, v20, vcc
	v_cmp_ngt_f32_e32 vcc, -1.0, v19
	s_nop 1
	v_cndmask_b32_e32 v20, v222, v20, vcc
	v_cmp_neq_f32_e32 vcc, -1.0, v19
	s_nop 1
	v_cndmask_b32_e32 v20, v219, v20, vcc
	v_cmp_lt_f32_e64 vcc, |v19|, s9
	s_nop 1
	v_cndmask_b32_e32 v19, v20, v19, vcc
	v_sub_f32_e32 v22, v22, v19
	global_store_dword v251, v22, s[52:53]
	v_add_f32_e32 v19, v249, v238
	v_min_f32_e32 v22, 0, v19
	v_mul_f32_e64 v19, |v19|, s3
	v_exp_f32_e32 v19, v19
	s_nop 0
	v_add_f32_e32 v23, 1.0, v19
	v_add_f32_e32 v20, -1.0, v23
	v_sub_f32_e32 v21, v20, v23
	v_add_f32_e32 v21, 1.0, v21
	v_sub_f32_e32 v20, v19, v20
	v_add_f32_e32 v24, v20, v21
	v_frexp_mant_f32_e32 v20, v23
	v_cmp_gt_f32_e32 vcc, s6, v20
	v_cvt_f64_f32_e32 v[20:21], v23
	v_frexp_exp_i32_f64_e32 v20, v[20:21]
	v_subbrev_co_u32_e32 v20, vcc, 0, v20, vcc
	v_sub_u32_e32 v21, 0, v20
	v_ldexp_f32 v23, v23, v21
	v_ldexp_f32 v21, v24, v21
	v_add_f32_e32 v24, -1.0, v23
	v_add_f32_e32 v25, 1.0, v24
	v_sub_f32_e32 v25, v23, v25
	v_add_f32_e32 v25, v21, v25
	v_add_f32_e32 v26, v24, v25
	v_sub_f32_e32 v24, v26, v24
	v_sub_f32_e32 v24, v25, v24
	v_add_f32_e32 v25, 1.0, v23
	v_add_f32_e32 v27, -1.0, v25
	v_sub_f32_e32 v23, v23, v27
	v_add_f32_e32 v21, v21, v23
	v_add_f32_e32 v23, v25, v21
	v_sub_f32_e32 v25, v23, v25
	v_sub_f32_e32 v21, v21, v25
	v_rcp_f32_e32 v25, v23
	v_cvt_f32_i32_e32 v20, v20
	v_cmp_neq_f32_e32 vcc, s8, v19
	v_mul_f32_e32 v27, v26, v25
	v_mul_f32_e32 v28, v23, v27
	v_fma_f32 v29, v27, v23, -v28
	v_fmac_f32_e32 v29, v27, v21
	v_add_f32_e32 v30, v28, v29
	v_sub_f32_e32 v31, v26, v30
	v_sub_f32_e32 v26, v26, v31
	v_sub_f32_e32 v28, v30, v28
	v_sub_f32_e32 v26, v26, v30
	v_add_f32_e32 v24, v24, v26
	v_sub_f32_e32 v26, v28, v29
	v_add_f32_e32 v24, v26, v24
	v_add_f32_e32 v26, v31, v24
	v_mul_f32_e32 v28, v25, v26
	v_mul_f32_e32 v29, v23, v28
	v_fma_f32 v23, v28, v23, -v29
	v_fmac_f32_e32 v23, v28, v21
	v_sub_f32_e32 v21, v31, v26
	v_add_f32_e32 v21, v24, v21
	v_add_f32_e32 v24, v29, v23
	v_sub_f32_e32 v30, v26, v24
	v_sub_f32_e32 v26, v26, v30
	v_sub_f32_e32 v29, v24, v29
	v_sub_f32_e32 v24, v26, v24
	v_add_f32_e32 v21, v21, v24
	v_sub_f32_e32 v23, v29, v23
	v_add_f32_e32 v21, v23, v21
	v_add_f32_e32 v23, v27, v28
	v_add_f32_e32 v21, v30, v21
	v_sub_f32_e32 v24, v23, v27
	v_mul_f32_e32 v21, v25, v21
	v_sub_f32_e32 v24, v28, v24
	v_add_f32_e32 v21, v24, v21
	v_mul_f32_e32 v27, 0x3f317218, v20
	v_add_f32_e32 v24, v23, v21
	v_fma_f32 v28, v20, s7, -v27
	v_mul_f32_e32 v25, v24, v24
	v_fmac_f32_e32 v28, 0xb102e308, v20
	v_sub_f32_e32 v20, v24, v23
	v_fmamk_f32 v26, v25, 0x3e9b6dac, v214
	v_sub_f32_e32 v20, v21, v20
	v_add_f32_e32 v21, v27, v28
	v_fmaak_f32 v26, v25, v26, 0x3f2aaada
	v_sub_f32_e32 v23, v21, v27
	v_ldexp_f32 v27, v24, 1
	v_mul_f32_e32 v24, v24, v25
	v_mul_f32_e32 v24, v24, v26
	v_add_f32_e32 v25, v27, v24
	v_sub_f32_e32 v26, v25, v27
	v_ldexp_f32 v20, v20, 1
	v_sub_f32_e32 v24, v24, v26
	v_add_f32_e32 v20, v20, v24
	v_add_f32_e32 v24, v25, v20
	v_sub_f32_e32 v25, v24, v25
	v_sub_f32_e32 v20, v20, v25
	v_add_f32_e32 v25, v21, v24
	v_sub_f32_e32 v26, v25, v21
	v_sub_f32_e32 v27, v25, v26
	v_sub_f32_e32 v23, v28, v23
	v_sub_f32_e32 v21, v21, v27
	v_sub_f32_e32 v24, v24, v26
	v_add_f32_e32 v21, v24, v21
	v_add_f32_e32 v24, v23, v20
	v_sub_f32_e32 v26, v24, v23
	v_sub_f32_e32 v27, v24, v26
	v_sub_f32_e32 v23, v23, v27
	v_sub_f32_e32 v20, v20, v26
	v_add_f32_e32 v21, v24, v21
	v_add_f32_e32 v20, v20, v23
	v_add_f32_e32 v23, v25, v21
	v_sub_f32_e32 v24, v23, v25
	v_sub_f32_e32 v21, v21, v24
	v_add_f32_e32 v20, v20, v21
	v_add_f32_e32 v20, v23, v20
	v_cndmask_b32_e32 v20, v221, v20, vcc
	v_cmp_ngt_f32_e32 vcc, -1.0, v19
	s_nop 1
	v_cndmask_b32_e32 v20, v222, v20, vcc
	v_cmp_neq_f32_e32 vcc, -1.0, v19
	s_nop 1
	v_cndmask_b32_e32 v20, v219, v20, vcc
	v_cmp_lt_f32_e64 vcc, |v19|, s9
	s_nop 1
	v_cndmask_b32_e32 v19, v20, v19, vcc
	v_sub_f32_e32 v22, v22, v19
	global_store_dword v246, v22, s[52:53]
